# online softmax: reference max moved only when tile max exceeds it by >8 (lazy rescale), table build split
# speedup vs baseline: 1.0183x; 1.0183x over previous
; DI void task_nsa(const P& p, int layer, int task, bf16_t* sm, int dm) {
;     ...
;   __syncthreads();
;   for (int i = tid; i < 4 * 129; i += NTHR) {
;     const int r = i / 129, d = i % 129;
;     tabs[r * 132 + d] = ((const float*)(p.ws + O_TABS))[(12 + g * 4 + r) * 132 + d];
.LBB0_654:
	s_or_b64 exec, exec, s[0:1]
	v_mov_b32_e32 v0, v195
	s_and_b32 s40, s34, 1
	s_movk_i32 s0, 0x204
	s_barrier
	s_mul_i32 s100, s40, 0x840
	s_addk_i32 s100, 0x18c0
	s_add_u32 s36, s20, s100
	s_addc_u32 s37, s21, 0
	s_movk_i32 s100, 0x80
	s_movk_i32 s101, 0x200
	v_subrev_u32_e32 v247, 64, v195
	v_add_u32_e32 v248, 0x1c0, v195
	v_med3_i32 v249, v247, 0, s100
	v_med3_i32 v250, v248, 0, s100
	v_lshlrev_b32_e32 v249, 2, v249
	v_lshlrev_b32_e32 v250, 2, v250
	global_load_dword v196, v249, s[36:37]
	global_load_dword v197, v250, s[36:37]
	global_load_dword v198, v249, s[36:37] offset:528
	global_load_dword v199, v250, s[36:37] offset:528
	global_load_dword v200, v249, s[36:37] offset:1056
	global_load_dword v201, v250, s[36:37] offset:1056
	global_load_dword v202, v249, s[36:37] offset:1584
	global_load_dword v203, v250, s[36:37] offset:1584
	s_lshl_b32 s6, s40, 2
	v_cmp_gt_i32_e32 vcc, s0, v0
	s_barrier
	s_and_saveexec_b64 s[0:1], vcc
	s_cbranch_execz .LBB0_662
	v_max_i32_e32 v1, 4, v0
	v_sub_u32_e32 v1, v1, v0
	v_add_u32_e32 v2, 0x1ff, v1
	s_movk_i32 s2, 0x1ff
	v_cmp_lt_u32_e32 vcc, s2, v2
	s_mov_b64 s[4:5], -1
	v_mov_b32_e32 v1, v0
	s_and_saveexec_b64 s[2:3], vcc
	s_cbranch_execz .LBB0_659
	v_lshrrev_b32_e32 v1, 9, v2
	v_add_u32_e32 v4, 1, v1
	s_add_i32 s7, s6, 12
	v_and_b32_e32 v5, 0xfffffe, v4
	v_add_u32_e32 v1, 0x200, v0
	s_mov_b32 s8, s7
	s_mov_b64 s[4:5], 0
	v_mov_b32_e32 v6, v5
	v_mov_b64_e32 v[2:3], v[0:1]

; DI void task_nsa(const P& p, int layer, int task, bf16_t* sm, int dm) {
;     ...
;   for (int i = tid; i < 4 * 129; i += NTHR) {
;     const int r = i / 129, d = i % 129;
;     tabs[r * 132 + d] = ((const float*)(p.ws + O_TABS))[(12 + g * 4 + r) * 132 + d];
;   }
;   for (int i = tid; i < 64 * 65; i += NTHR) cbuf[i] = 0.f;
.LBB0_662:
	s_or_b64 exec, exec, s[0:1]
	v_mov_b32_e32 v246, 0xf149f2ca
	v_lshlrev_b32_e32 v244, 2, v195
	v_add_u32_e32 v244, 0x1e000, v244
	s_waitcnt vmcnt(0)
	v_cmp_gt_u32_e64 s[98:99], s101, v247
	s_nop 1
	v_cndmask_b32_e64 v196, v246, v196, s[98:99]
	v_cndmask_b32_e64 v198, v246, v198, s[98:99]
	v_cndmask_b32_e64 v200, v246, v200, s[98:99]
	v_cndmask_b32_e64 v202, v246, v202, s[98:99]
	v_cmp_gt_u32_e64 s[98:99], s101, v248
	s_nop 1
	v_cndmask_b32_e64 v197, v246, v197, s[98:99]
	v_cndmask_b32_e64 v199, v246, v199, s[98:99]
	v_cndmask_b32_e64 v201, v246, v201, s[98:99]
	v_cndmask_b32_e64 v203, v246, v203, s[98:99]
	ds_write_b32 v244, v196
	ds_write_b32 v244, v197 offset:2048
	ds_write_b32 v244, v198 offset:4096
	ds_write_b32 v244, v199 offset:6144
	ds_write_b32 v244, v200 offset:8192
	ds_write_b32 v244, v201 offset:10240
	ds_write_b32 v244, v202 offset:12288
	ds_write_b32 v244, v203 offset:14336
	s_movk_i32 s0, 0x1040
	v_cmp_gt_i32_e32 vcc, s0, v0
	s_and_saveexec_b64 s[0:1], vcc
	s_cbranch_execz .LBB0_665
	v_readlane_b32 s2, v255, 3
	v_add_u32_e32 v2, 0xfffffe00, v0
	s_nop 0
	v_lshl_add_u32 v1, v0, 2, s2
	s_mov_b64 s[2:3], 0

; DI float ex2(float x) { return __builtin_amdgcn_exp2f(x); }
; DI float xor32(float v) { return __shfl_xor(v, 32); }
; template <int NDT, int MODE, bool ALLON>
; DI void attn_tile(const bf16_t* Kl, int kst, const bf16_t* Vl, const bf16x8 (&q)[4], f32x16 (&O)[NDT], float& m, float& l,
;                   int kbase, int qp, int win, float cbias, const float* tab, bool lane_on) {
;     ...
;     float tmax = -1e30f;
; #pragma unroll
;     for (int st = 0; st < 2; ++st)
; #pragma unroll
;       for (int i = 0; i < 16; ++i) {
;         const int key = kbase + st * 32 + 8 * (i >> 2) + 4 * lh + (i & 3);
;         float v;
;         if (MODE == 1) {
;           const int dist = qp - key;
;           const bool ok = (ALLON || lane_on) && dist >= 0 && dist < win;
;           const int di = dist < 0 ? 0 : (dist > 128 ? 128 : dist);
;           v = ok ? s[st][i] + tab[di] : -1e30f;
;         } else {
;           v = (16 * key + 31 <= qp) ? s[st][i] : -1e30f;
;         }
;         s[st][i] = v;
;         tmax = fmaxf(tmax, v);
;       }
;     tmax = fmaxf(tmax, xor32(tmax));
;     const float mn = fmaxf(m, tmax);
;     alpha = ex2(m - mn);
.LBB0_668:
	v_mov_b32_e32 v32, v195
	s_waitcnt lgkmcnt(0)
	s_barrier
	s_nop 0
	v_and_b32_e32 v33, 31, v32
	v_bfe_u32 v141, v32, 5, 1
	v_mul_u32_u24_e32 v32, 0x48, v33
	v_lshlrev_b32_e32 v139, 1, v32
	v_lshlrev_b32_e32 v32, 4, v141
	v_add3_u32 v91, s7, v139, v32
	ds_read_b128 v[32:35], v91 offset:4608
	ds_read_b128 v[36:39], v91
	ds_read_b128 v[142:145], v91 offset:32
	s_waitcnt lgkmcnt(1)
	v_mfma_f32_32x32x16_bf16 v[48:63], v[36:39], v[64:67], 0
	ds_read_b128 v[146:149], v91 offset:4640
	v_mfma_f32_32x32x16_bf16 v[32:47], v[32:35], v[64:67], 0
	s_waitcnt lgkmcnt(1)
	v_mfma_f32_32x32x16_bf16 v[48:63], v[142:145], v[68:71], v[48:63]
	s_waitcnt lgkmcnt(0)
	v_mfma_f32_32x32x16_bf16 v[32:47], v[146:149], v[68:71], v[32:47]
	ds_read_b128 v[142:145], v91 offset:64
	ds_read_b128 v[146:149], v91 offset:4672
	s_waitcnt lgkmcnt(1)
	v_mfma_f32_32x32x16_bf16 v[48:63], v[142:145], v[72:75], v[48:63]
	s_waitcnt lgkmcnt(0)
	v_mfma_f32_32x32x16_bf16 v[32:47], v[146:149], v[72:75], v[32:47]
	ds_read_b128 v[142:145], v91 offset:96
	ds_read_b128 v[146:149], v91 offset:4704
	v_lshl_add_u32 v91, v141, 6, s5
	s_waitcnt lgkmcnt(1)
	v_mfma_f32_32x32x16_bf16 v[48:63], v[142:145], v[76:79], v[48:63]
	v_add_u32_e32 v142, 0xfffffc50, v91
	v_cmp_le_i32_e32 vcc, v142, v135
	s_waitcnt lgkmcnt(0)
	v_mfma_f32_32x32x16_bf16 v[32:47], v[146:149], v[76:79], v[32:47]
	s_nop 7
	v_cndmask_b32_e32 v152, v232, v48, vcc
	v_add_u32_e32 v48, 0xfffffc60, v91
	v_cmp_le_i32_e32 vcc, v48, v135
	s_nop 1
	v_cndmask_b32_e32 v153, v232, v49, vcc
	v_add_u32_e32 v49, 0xfffffc70, v91
	v_cmp_le_i32_e32 vcc, v49, v135
	v_add_u32_e32 v49, 0xfffffc80, v91
	v_max3_f32 v48, v152, s93, v153
	v_cndmask_b32_e32 v150, v232, v50, vcc
	v_cmp_le_i32_e32 vcc, v49, v135
	v_add_u32_e32 v49, 0xfffffcd0, v91
	s_nop 0
	v_cndmask_b32_e32 v148, v232, v51, vcc
	v_cmp_le_i32_e32 vcc, v49, v135
	v_add_u32_e32 v49, 0xfffffce0, v91
	v_max3_f32 v48, v48, v150, v148
	v_cndmask_b32_e32 v147, v232, v52, vcc
	v_cmp_le_i32_e32 vcc, v49, v135
	v_add_u32_e32 v49, 0xfffffcf0, v91
	s_nop 0
	v_cndmask_b32_e32 v145, v232, v53, vcc
	v_cmp_le_i32_e32 vcc, v49, v135
	v_add_u32_e32 v49, 0xfffffd00, v91
	v_max3_f32 v48, v48, v147, v145
	v_cndmask_b32_e32 v144, v232, v54, vcc
	v_cmp_le_i32_e32 vcc, v49, v135
	v_add_u32_e32 v49, 0xfffffd50, v91
	s_nop 0
	v_cndmask_b32_e32 v154, v232, v55, vcc
	v_cmp_le_i32_e32 vcc, v49, v135
	v_add_u32_e32 v49, 0xfffffd60, v91
	v_max3_f32 v48, v48, v144, v154
	v_cndmask_b32_e32 v151, v232, v56, vcc
	v_cmp_le_i32_e32 vcc, v49, v135
	v_add_u32_e32 v49, 0xfffffd70, v91
	s_nop 0
	v_cndmask_b32_e32 v149, v232, v57, vcc
	v_cmp_le_i32_e32 vcc, v49, v135
	v_add_u32_e32 v49, 0xfffffd80, v91
	v_max3_f32 v48, v48, v151, v149
	v_cndmask_b32_e32 v146, v232, v58, vcc
	v_cmp_le_i32_e32 vcc, v49, v135
	v_add_u32_e32 v49, 0xfffffdd0, v91
	s_nop 0
	v_cndmask_b32_e32 v143, v232, v59, vcc
	v_cmp_le_i32_e32 vcc, v49, v135
	v_add_u32_e32 v49, 0xfffffde0, v91
	v_max3_f32 v48, v48, v146, v143
	v_cndmask_b32_e32 v142, v232, v60, vcc
	v_cmp_le_i32_e32 vcc, v49, v135
	v_add_u32_e32 v49, 0xfffffdf0, v91
	s_nop 0
	v_cndmask_b32_e32 v57, v232, v61, vcc
	v_cmp_le_i32_e32 vcc, v49, v135
	v_add_u32_e32 v49, 0xfffffe00, v91
	v_max3_f32 v48, v48, v142, v57
	v_cndmask_b32_e32 v60, v232, v62, vcc
	v_cmp_le_i32_e32 vcc, v49, v135
	v_add_u32_e32 v49, 0xfffffe50, v91
	s_nop 0
	v_cndmask_b32_e32 v61, v232, v63, vcc
	v_cmp_le_i32_e32 vcc, v49, v135
	v_max3_f32 v48, v48, v60, v61
	s_nop 0
	v_cndmask_b32_e32 v58, v232, v32, vcc
	v_add_u32_e32 v32, 0xfffffe60, v91
	v_cmp_le_i32_e32 vcc, v32, v135
	s_nop 1
	v_cndmask_b32_e32 v55, v232, v33, vcc
	v_add_u32_e32 v33, 0xfffffe70, v91
	v_cmp_le_i32_e32 vcc, v33, v135
	v_add_u32_e32 v33, 0xfffffe80, v91
	v_max3_f32 v32, v48, v58, v55
	v_cndmask_b32_e32 v54, v232, v34, vcc
	v_cmp_le_i32_e32 vcc, v33, v135
	v_add_u32_e32 v33, 0xfffffed0, v91
	v_and_b32_e32 v34, 64, v231
	v_cndmask_b32_e32 v53, v232, v35, vcc
	v_cmp_le_i32_e32 vcc, v33, v135
	v_add_u32_e32 v33, 0xfffffee0, v91
	v_max3_f32 v32, v32, v54, v53
	v_cndmask_b32_e32 v52, v232, v36, vcc
	v_cmp_le_i32_e32 vcc, v33, v135
	v_add_u32_e32 v33, 0xfffffef0, v91
	v_add_u32_e32 v34, 64, v34
	v_cndmask_b32_e32 v51, v232, v37, vcc
	v_cmp_le_i32_e32 vcc, v33, v135
	v_add_u32_e32 v33, 0xffffff00, v91
	v_max3_f32 v32, v32, v52, v51
	v_cndmask_b32_e32 v50, v232, v38, vcc
	v_cmp_le_i32_e32 vcc, v33, v135
	v_add_u32_e32 v33, 0xffffff50, v91
	s_nop 0
	v_cndmask_b32_e32 v49, v232, v39, vcc
	v_cmp_le_i32_e32 vcc, v33, v135
	v_add_u32_e32 v33, 0xffffff60, v91
	v_max3_f32 v32, v32, v50, v49
	v_cndmask_b32_e32 v48, v232, v40, vcc
	v_cmp_le_i32_e32 vcc, v33, v135
	v_add_u32_e32 v33, 0xffffff70, v91
	s_nop 0
	v_cndmask_b32_e32 v41, v232, v41, vcc
	v_cmp_le_i32_e32 vcc, v33, v135
	v_add_u32_e32 v33, 0xffffff80, v91
	v_max3_f32 v32, v32, v48, v41
	v_cndmask_b32_e32 v40, v232, v42, vcc
	v_cmp_le_i32_e32 vcc, v33, v135
	v_subrev_u32_e32 v33, 48, v91
	s_nop 0
	v_cndmask_b32_e32 v39, v232, v43, vcc
	v_cmp_le_i32_e32 vcc, v33, v135
	v_subrev_u32_e32 v33, 32, v91
	v_max3_f32 v32, v32, v40, v39
	v_cndmask_b32_e32 v38, v232, v44, vcc
	v_cmp_le_i32_e32 vcc, v33, v135
	v_add_u32_e32 v33, -16, v91
	s_nop 0
	v_cndmask_b32_e32 v37, v232, v45, vcc
	v_cmp_le_i32_e32 vcc, v33, v135
	v_xor_b32_e32 v33, 32, v231
	v_max3_f32 v32, v32, v38, v37
	v_cndmask_b32_e32 v36, v232, v46, vcc
	v_cmp_le_i32_e32 vcc, v91, v135
	s_nop 1
	v_cndmask_b32_e32 v35, v232, v47, vcc
	v_cmp_lt_i32_e32 vcc, v33, v34
	v_max3_f32 v32, v32, v36, v35
	s_nop 0
	v_cndmask_b32_e32 v33, v231, v33, vcc
	v_lshlrev_b32_e32 v91, 2, v33
	ds_bpermute_b32 v33, v91, v32
	s_waitcnt lgkmcnt(0)
	v_max_f32_e32 v32, v32, v33
	v_add_f32_e32 v33, 0x41000000, v140
	v_cmp_gt_f32_e32 vcc, v32, v33
	s_nop 1
	v_cndmask_b32_e32 v33, v140, v32, vcc
	v_sub_f32_e32 v32, v140, v33
	v_exp_f32_e32 v32, v32
	s_nop 0
	v_cmp_neq_f32_e32 vcc, 1.0, v32
	s_cbranch_vccz .LBB0_670
	v_pk_mul_f32 v[0:1], v[112:113], v[32:33] op_sel_hi:[1,0]
	v_pk_mul_f32 v[2:3], v[114:115], v[32:33] op_sel_hi:[1,0]
	v_pk_mul_f32 v[4:5], v[116:117], v[32:33] op_sel_hi:[1,0]
	v_pk_mul_f32 v[6:7], v[118:119], v[32:33] op_sel_hi:[1,0]
	v_pk_mul_f32 v[8:9], v[120:121], v[32:33] op_sel_hi:[1,0]
	v_pk_mul_f32 v[10:11], v[122:123], v[32:33] op_sel_hi:[1,0]
	v_pk_mul_f32 v[12:13], v[124:125], v[32:33] op_sel_hi:[1,0]
	v_pk_mul_f32 v[14:15], v[126:127], v[32:33] op_sel_hi:[1,0]
	v_pk_mul_f32 v[16:17], v[96:97], v[32:33] op_sel_hi:[1,0]
	v_pk_mul_f32 v[18:19], v[98:99], v[32:33] op_sel_hi:[1,0]
	v_pk_mul_f32 v[20:21], v[100:101], v[32:33] op_sel_hi:[1,0]
	v_pk_mul_f32 v[22:23], v[102:103], v[32:33] op_sel_hi:[1,0]
	v_pk_mul_f32 v[24:25], v[104:105], v[32:33] op_sel_hi:[1,0]
	v_pk_mul_f32 v[26:27], v[106:107], v[32:33] op_sel_hi:[1,0]
	v_pk_mul_f32 v[28:29], v[108:109], v[32:33] op_sel_hi:[1,0]
	v_pk_mul_f32 v[30:31], v[110:111], v[32:33] op_sel_hi:[1,0]

; #define MFMA32(a, b, c) __builtin_amdgcn_mfma_f32_32x32x16_bf16((a), (b), (c), 0, 0, 0)
; DI float ex2(float x) { return __builtin_amdgcn_exp2f(x); }
; DI float xor32(float v) { return __shfl_xor(v, 32); }
; template <int NDT, int MODE, bool ALLON>
; DI void attn_tile(const bf16_t* Kl, int kst, const bf16_t* Vl, const bf16x8 (&q)[4], f32x16 (&O)[NDT], float& m, float& l,
;                   int kbase, int qp, int win, float cbias, const float* tab, bool lane_on) {
;     ...
;   for (int ks = 0; ks < 4; ++ks) {
;     const bf16x8 k0 = *(const bf16x8*)(Kl + lr * kst + ks * 16 + lh * 8);
;     const bf16x8 k1 = *(const bf16x8*)(Kl + (32 + lr) * kst + ks * 16 + lh * 8);
;     s[0] = MFMA32(k0, q[ks], s[0]);
;     s[1] = MFMA32(k1, q[ks], s[1]);
;   }
;   float alpha, psum = 0.f;
;   if (MODE == 0) {
;     float tmax = fmaxf(s[0][0], s[1][0]);
; #pragma unroll
;     for (int i = 1; i < 16; ++i) tmax = fmaxf(tmax, fmaxf(s[0][i], s[1][i]));
;     tmax = fmaxf(tmax, xor32(tmax)) + cbias;
;     if (!ALLON) tmax = lane_on ? tmax : -1e30f;
;     const float mn = fmaxf(m, tmax);
;     alpha = ex2(m - mn);
;     m = mn;
; DI void task_nsa(const P& p, int layer, int task, bf16_t* sm, int dm) {
;     ...
;     for (; todo; ++itc) {
;       const int j = __ffsll((long long)todo) - 1;
;       todo &= todo - 1ull;
;       bf16_t* Kl = sm + (itc & 1) * 9216; bf16_t* Vl = Kl + 4608;
;       kv_lstore(R, Kl, Vl);
;       if (todo) kv_gload(R, kg, 128, vg, S_, (__ffsll((long long)todo) - 1) * 64);
;       __syncthreads();
;       const bool on = (mymask >> j) & 1ull;
;       if (j * 64 <= qmin + 31 && __ballot(on)) {
;         if (j * 64 + 63 + 128 <= qmin)
;           attn_tile<2, 0, false>(Kl, 72, Vl, q, O, m, l, j * 64, qp, 0, tab[128], tab, on);
.LBB0_720:
	v_ffbl_b32_e32 v1, v1
	v_ffbl_b32_e32 v0, v0
	v_add_u32_e64 v1, v1, 32 clamp
	v_min_u32_e32 v0, v1, v0
	v_lshlrev_b32_e32 v32, 6, v0
	v_cmp_le_i32_e32 vcc, v32, v138
	s_waitcnt lgkmcnt(0)
	s_barrier
	s_and_saveexec_b64 s[8:9], vcc
	s_cbranch_execz .LBB0_797
	v_lshrrev_b64 v[0:1], v0, v[96:97]
	v_and_b32_e32 v0, 1, v0
	v_cmp_eq_u32_e64 s[4:5], 1, v0
	v_cmp_ne_u32_e32 vcc, 0, v0
	s_cbranch_vccz .LBB0_797
	v_cmp_le_i32_e32 vcc, v32, v137
	s_and_saveexec_b64 s[28:29], vcc
	s_xor_b64 s[28:29], exec, s[28:29]
	s_cbranch_execz .LBB0_727
	v_mov_b32_e32 v0, v195
	ds_read_b32 v144, v135 offset:37376
	s_nop 0
	v_and_b32_e32 v1, 31, v0
	v_lshrrev_b32_e32 v0, 2, v0
	v_mul_u32_u24_e32 v1, 0x48, v1
	v_and_b32_e32 v143, 8, v0
	v_lshlrev_b32_e32 v142, 1, v1
	v_lshlrev_b32_e32 v0, 1, v143
	v_add3_u32 v4, s45, v142, v0
	ds_read_b128 v[0:3], v4
	s_waitcnt lgkmcnt(0)
	v_mfma_f32_32x32x16_bf16 v[48:63], v[0:3], v[64:67], 0
	ds_read_b128 v[0:3], v4 offset:4608
	s_waitcnt lgkmcnt(0)
	v_mfma_f32_32x32x16_bf16 v[32:47], v[0:3], v[64:67], 0
	ds_read_b128 v[0:3], v4 offset:32
	s_waitcnt lgkmcnt(0)
	v_mfma_f32_32x32x16_bf16 v[48:63], v[0:3], v[68:71], v[48:63]
	ds_read_b128 v[0:3], v4 offset:4640
	s_waitcnt lgkmcnt(0)
	v_mfma_f32_32x32x16_bf16 v[32:47], v[0:3], v[68:71], v[32:47]
	ds_read_b128 v[0:3], v4 offset:64
	s_waitcnt lgkmcnt(0)
	v_mfma_f32_32x32x16_bf16 v[48:63], v[0:3], v[72:75], v[48:63]
	ds_read_b128 v[0:3], v4 offset:4672
	s_waitcnt lgkmcnt(0)
	v_mfma_f32_32x32x16_bf16 v[32:47], v[0:3], v[72:75], v[32:47]
	ds_read_b128 v[0:3], v4 offset:4704
	s_waitcnt lgkmcnt(0)
	v_mfma_f32_32x32x16_bf16 v[32:47], v[0:3], v[76:79], v[32:47]
	ds_read_b128 v[0:3], v4 offset:96
	s_waitcnt lgkmcnt(0)
	v_mfma_f32_32x32x16_bf16 v[48:63], v[0:3], v[76:79], v[48:63]
	s_nop 8
	v_max3_f32 v0, v32, v33, v34
	v_max3_f32 v0, v0, v35, v36
	v_max3_f32 v0, v0, v37, v38
	v_max3_f32 v0, v0, v39, v40
	v_max3_f32 v0, v0, v41, v42
	v_max3_f32 v0, v0, v43, v44
	v_max3_f32 v0, v0, v45, v46
	v_max_f32_e32 v0, v0, v47
	v_max3_f32 v1, v48, v49, v50
	v_max3_f32 v1, v1, v51, v52
	v_max3_f32 v1, v1, v53, v54
	v_max3_f32 v1, v1, v55, v56
	v_max3_f32 v1, v1, v57, v58
	v_max3_f32 v1, v1, v59, v60
	v_max3_f32 v1, v1, v61, v62
	v_max_f32_e32 v1, v1, v63
	v_max_f32_e32 v0, v0, v1
	ds_bpermute_b32 v1, v91, v0
	s_waitcnt lgkmcnt(0)
	v_max_f32_e32 v1, v1, v1
	v_max_f32_e32 v0, v0, v1
	v_add_f32_e32 v0, v144, v0
	v_cndmask_b32_e64 v0, v232, v0, s[4:5]
	v_add_f32_e32 v1, 0x41000000, v88
	v_cmp_gt_f32_e32 vcc, v0, v1
	s_nop 1
	v_cndmask_b32_e32 v141, v88, v0, vcc
	v_sub_f32_e32 v0, v88, v141
	v_exp_f32_e32 v88, v0
	s_nop 0
	v_cmp_neq_f32_e32 vcc, 1.0, v88
	s_cbranch_vccz .LBB0_799
	v_pk_mul_f32 v[160:161], v[160:161], v[88:89] op_sel_hi:[1,0]
	v_pk_mul_f32 v[162:163], v[162:163], v[88:89] op_sel_hi:[1,0]
	v_pk_mul_f32 v[164:165], v[164:165], v[88:89] op_sel_hi:[1,0]
	v_pk_mul_f32 v[166:167], v[166:167], v[88:89] op_sel_hi:[1,0]
	v_pk_mul_f32 v[168:169], v[168:169], v[88:89] op_sel_hi:[1,0]
	v_pk_mul_f32 v[170:171], v[170:171], v[88:89] op_sel_hi:[1,0]
	v_pk_mul_f32 v[172:173], v[172:173], v[88:89] op_sel_hi:[1,0]
	v_pk_mul_f32 v[174:175], v[174:175], v[88:89] op_sel_hi:[1,0]
	v_pk_mul_f32 v[176:177], v[176:177], v[88:89] op_sel_hi:[1,0]
	v_pk_mul_f32 v[178:179], v[178:179], v[88:89] op_sel_hi:[1,0]
	v_pk_mul_f32 v[180:181], v[180:181], v[88:89] op_sel_hi:[1,0]
	v_pk_mul_f32 v[182:183], v[182:183], v[88:89] op_sel_hi:[1,0]
	v_pk_mul_f32 v[184:185], v[184:185], v[88:89] op_sel_hi:[1,0]
	v_pk_mul_f32 v[186:187], v[186:187], v[88:89] op_sel_hi:[1,0]
	v_pk_mul_f32 v[188:189], v[188:189], v[88:89] op_sel_hi:[1,0]
	v_pk_mul_f32 v[190:191], v[190:191], v[88:89] op_sel_hi:[1,0]
	s_cbranch_execnz .LBB0_726

; #define MFMA32(a, b, c) __builtin_amdgcn_mfma_f32_32x32x16_bf16((a), (b), (c), 0, 0, 0)
; DI float ex2(float x) { return __builtin_amdgcn_exp2f(x); }
; DI float xor32(float v) { return __shfl_xor(v, 32); }
; template <int NDT, int MODE, bool ALLON>
; DI void attn_tile(const bf16_t* Kl, int kst, const bf16_t* Vl, const bf16x8 (&q)[4], f32x16 (&O)[NDT], float& m, float& l,
;                   int kbase, int qp, int win, float cbias, const float* tab, bool lane_on) {
;     ...
;   for (int ks = 0; ks < 4; ++ks) {
;     const bf16x8 k0 = *(const bf16x8*)(Kl + lr * kst + ks * 16 + lh * 8);
;     const bf16x8 k1 = *(const bf16x8*)(Kl + (32 + lr) * kst + ks * 16 + lh * 8);
;     s[0] = MFMA32(k0, q[ks], s[0]);
;     s[1] = MFMA32(k1, q[ks], s[1]);
;   }
;   float alpha, psum = 0.f;
;   if (MODE == 0) {
;     float tmax = fmaxf(s[0][0], s[1][0]);
; #pragma unroll
;     for (int i = 1; i < 16; ++i) tmax = fmaxf(tmax, fmaxf(s[0][i], s[1][i]));
;     tmax = fmaxf(tmax, xor32(tmax)) + cbias;
;     if (!ALLON) tmax = lane_on ? tmax : -1e30f;
;     const float mn = fmaxf(m, tmax);
;     alpha = ex2(m - mn);
;     m = mn;
;     const float mc = (ALLON || lane_on) ? mn - cbias : 1e30f;
; #pragma unroll
;     for (int st = 0; st < 2; ++st)
; #pragma unroll
;       for (int i = 0; i < 16; ++i) { const float pe = ex2(s[st][i] - mc); psum += pe; s[st][i] = pe; }
;   } else {
;     float tmax = -1e30f;
; #pragma unroll
;     for (int st = 0; st < 2; ++st)
; #pragma unroll
;       for (int i = 0; i < 16; ++i) {
;         const int key = kbase + st * 32 + 8 * (i >> 2) + 4 * lh + (i & 3);
;         float v;
;         if (MODE == 1) {
;           const int dist = qp - key;
;           const bool ok = (ALLON || lane_on) && dist >= 0 && dist < win;
;           const int di = dist < 0 ? 0 : (dist > 128 ? 128 : dist);
;           v = ok ? s[st][i] + tab[di] : -1e30f;
;         } else {
;           v = (16 * key + 31 <= qp) ? s[st][i] : -1e30f;
;         }
;         s[st][i] = v;
;         tmax = fmaxf(tmax, v);
;       }
;     tmax = fmaxf(tmax, xor32(tmax));
;     const float mn = fmaxf(m, tmax);
;     alpha = ex2(m - mn);
.LBB0_727:
	s_andn2_saveexec_b64 s[28:29], s[28:29]
	s_cbranch_execz .LBB0_796
	s_nop 6
	v_mov_b32_e32 v0, v195
	v_mov_b32_e32 v55, 0xf149f2ca
	v_and_b32_e32 v1, 31, v0
	v_bfe_u32 v42, v0, 5, 1
	v_mul_u32_u24_e32 v0, 0x48, v1
	v_lshlrev_b32_e32 v33, 1, v0
	v_lshlrev_b32_e32 v0, 4, v42
	v_add3_u32 v43, s45, v33, v0
	ds_read_b128 v[0:3], v43 offset:4608
	ds_read_b128 v[4:7], v43
	ds_read_b128 v[34:37], v43 offset:32
	ds_read_b128 v[38:41], v43 offset:4640
	s_waitcnt lgkmcnt(2)
	v_mfma_f32_32x32x16_bf16 v[16:31], v[4:7], v[64:67], 0
	v_mov_b32_e32 v62, 0xf149f2ca
	v_mfma_f32_32x32x16_bf16 v[0:15], v[0:3], v[64:67], 0
	s_waitcnt lgkmcnt(1)
	v_mfma_f32_32x32x16_bf16 v[16:31], v[34:37], v[68:71], v[16:31]
	s_waitcnt lgkmcnt(0)
	v_mfma_f32_32x32x16_bf16 v[0:15], v[38:41], v[68:71], v[0:15]
	ds_read_b128 v[34:37], v43 offset:64
	ds_read_b128 v[38:41], v43 offset:4672
	s_waitcnt lgkmcnt(1)
	v_mfma_f32_32x32x16_bf16 v[16:31], v[34:37], v[72:75], v[16:31]
	s_waitcnt lgkmcnt(0)
	v_mfma_f32_32x32x16_bf16 v[0:15], v[38:41], v[72:75], v[0:15]
	ds_read_b128 v[34:37], v43 offset:96
	ds_read_b128 v[38:41], v43 offset:4704
	s_waitcnt lgkmcnt(1)
	v_mfma_f32_32x32x16_bf16 v[16:31], v[34:37], v[76:79], v[16:31]
	v_lshlrev_b32_e32 v34, 2, v42
	v_or_b32_e32 v32, v34, v32
	v_sub_u32_e32 v35, v134, v32
	v_bfe_u32 v245, v195, 6, 2
	v_lshlrev_b32_e32 v245, 12, v245
	v_add_u32_e32 v245, 0x1e014, v245
	v_lshl_add_u32 v244, v35, 2, v245
	v_subrev_u32_e32 v246, 20, v245
	v_cndmask_b32_e64 v244, v246, v244, s[4:5]
	s_waitcnt lgkmcnt(0)
	v_mfma_f32_32x32x16_bf16 v[0:15], v[38:41], v[76:79], v[0:15]
	ds_read2_b32 v[196:197], v244 offset0:59 offset1:58
	ds_read2_b32 v[198:199], v244 offset0:57 offset1:56
	ds_read2_b32 v[200:201], v244 offset0:51 offset1:50
	ds_read2_b32 v[202:203], v244 offset0:49 offset1:48
	ds_read2_b32 v[204:205], v244 offset0:43 offset1:42
	ds_read2_b32 v[206:207], v244 offset0:41 offset1:40
	ds_read2_b32 v[208:209], v244 offset0:35 offset1:34
	ds_read2_b32 v[210:211], v244 offset0:33 offset1:32
	ds_read2_b32 v[212:213], v244 offset0:27 offset1:26
	ds_read2_b32 v[214:215], v244 offset0:25 offset1:24
	ds_read2_b32 v[216:217], v244 offset0:19 offset1:18
	ds_read2_b32 v[218:219], v244 offset0:17 offset1:16
	ds_read2_b32 v[236:237], v244 offset0:11 offset1:10
	ds_read2_b32 v[238:239], v244 offset0:9 offset1:8
	ds_read2_b32 v[240:241], v244 offset0:3 offset1:2
	s_waitcnt lgkmcnt(14)
	v_add_f32_e32 v62, v16, v196
	v_add_f32_e32 v55, v17, v197
	ds_read2_b32 v[242:243], v244 offset0:1 offset1:0
	s_waitcnt lgkmcnt(14)
	v_add_f32_e32 v61, v18, v198
	v_add_f32_e32 v49, v19, v199
	s_waitcnt lgkmcnt(13)
	v_add_f32_e32 v60, v20, v200
	v_add_f32_e32 v47, v21, v201
	s_waitcnt lgkmcnt(12)
	v_add_f32_e32 v59, v22, v202
	v_add_f32_e32 v45, v23, v203
	s_waitcnt lgkmcnt(11)
	v_add_f32_e32 v58, v24, v204
	v_add_f32_e32 v43, v25, v205
	s_waitcnt lgkmcnt(10)
	v_add_f32_e32 v57, v26, v206
	v_add_f32_e32 v42, v27, v207
	s_waitcnt lgkmcnt(9)
	v_add_f32_e32 v56, v28, v208
	v_add_f32_e32 v41, v29, v209
	s_waitcnt lgkmcnt(8)
	v_add_f32_e32 v54, v30, v210
	v_add_f32_e32 v40, v31, v211
	s_waitcnt lgkmcnt(7)
	v_add_f32_e32 v52, v0, v212
	v_add_f32_e32 v39, v1, v213
	s_waitcnt lgkmcnt(6)
	v_add_f32_e32 v51, v2, v214
	v_add_f32_e32 v38, v3, v215
	s_waitcnt lgkmcnt(5)
	v_add_f32_e32 v48, v4, v216
	v_add_f32_e32 v37, v5, v217
	s_waitcnt lgkmcnt(4)
	v_add_f32_e32 v46, v6, v218
	v_add_f32_e32 v35, v7, v219
	s_waitcnt lgkmcnt(3)
	v_add_f32_e32 v44, v8, v236
	v_add_f32_e32 v36, v9, v237
	s_waitcnt lgkmcnt(2)
	v_add_f32_e32 v53, v10, v238
	v_add_f32_e32 v50, v11, v239
	s_waitcnt lgkmcnt(1)
	v_add_f32_e32 v142, v12, v240
	v_add_f32_e32 v63, v13, v241
	s_waitcnt lgkmcnt(0)
	v_add_f32_e32 v144, v14, v242
	v_add_f32_e32 v143, v15, v243
	v_max3_f32 v0, v62, s93, v55
	v_max3_f32 v0, v0, v61, v49
	v_max3_f32 v0, v0, v60, v47
	v_max3_f32 v0, v0, v59, v45
	v_max3_f32 v0, v0, v58, v43
	v_max3_f32 v0, v0, v57, v42
	v_max3_f32 v0, v0, v56, v41
	v_max3_f32 v0, v0, v54, v40
	v_max3_f32 v0, v0, v52, v39
	v_max3_f32 v0, v0, v51, v38
	v_max3_f32 v0, v0, v48, v37
	v_max3_f32 v0, v0, v46, v35
	v_max3_f32 v0, v0, v44, v36
	v_max3_f32 v0, v0, v53, v50
	v_max3_f32 v0, v0, v142, v63
	v_max3_f32 v0, v0, v144, v143
	ds_bpermute_b32 v1, v91, v0
	s_waitcnt lgkmcnt(0)
	v_max_f32_e32 v0, v0, v1
	v_add_f32_e32 v1, 0x41000000, v88
	v_cmp_gt_f32_e32 vcc, v0, v1
	s_nop 1
	v_cndmask_b32_e32 v141, v88, v0, vcc
	v_sub_f32_e32 v0, v88, v141
	v_exp_f32_e32 v32, v0
	s_nop 0
	v_cmp_neq_f32_e32 vcc, 1.0, v32
	s_cbranch_vccz .LBB0_800
	v_pk_mul_f32 v[160:161], v[160:161], v[32:33] op_sel_hi:[1,0]
	v_pk_mul_f32 v[162:163], v[162:163], v[32:33] op_sel_hi:[1,0]
	v_pk_mul_f32 v[164:165], v[164:165], v[32:33] op_sel_hi:[1,0]
	v_pk_mul_f32 v[166:167], v[166:167], v[32:33] op_sel_hi:[1,0]
	v_pk_mul_f32 v[168:169], v[168:169], v[32:33] op_sel_hi:[1,0]
	v_pk_mul_f32 v[170:171], v[170:171], v[32:33] op_sel_hi:[1,0]
	v_pk_mul_f32 v[172:173], v[172:173], v[32:33] op_sel_hi:[1,0]
	v_pk_mul_f32 v[174:175], v[174:175], v[32:33] op_sel_hi:[1,0]
	v_pk_mul_f32 v[176:177], v[176:177], v[32:33] op_sel_hi:[1,0]
	v_pk_mul_f32 v[178:179], v[178:179], v[32:33] op_sel_hi:[1,0]
	v_pk_mul_f32 v[180:181], v[180:181], v[32:33] op_sel_hi:[1,0]
	v_pk_mul_f32 v[182:183], v[182:183], v[32:33] op_sel_hi:[1,0]
	v_pk_mul_f32 v[184:185], v[184:185], v[32:33] op_sel_hi:[1,0]
	v_pk_mul_f32 v[186:187], v[186:187], v[32:33] op_sel_hi:[1,0]
	v_pk_mul_f32 v[188:189], v[188:189], v[32:33] op_sel_hi:[1,0]
	v_pk_mul_f32 v[190:191], v[190:191], v[32:33] op_sel_hi:[1,0]
	s_cbranch_execnz .LBB0_795

; #define MFMA32(a, b, c) __builtin_amdgcn_mfma_f32_32x32x16_bf16((a), (b), (c), 0, 0, 0)
; DI float ex2(float x) { return __builtin_amdgcn_exp2f(x); }
; DI float xor32(float v) { return __shfl_xor(v, 32); }
; template <int NDT, int MODE, bool ALLON>
; DI void attn_tile(const bf16_t* Kl, int kst, const bf16_t* Vl, const bf16x8 (&q)[4], f32x16 (&O)[NDT], float& m, float& l,
;                   int kbase, int qp, int win, float cbias, const float* tab, bool lane_on) {
;     ...
;   for (int ks = 0; ks < 4; ++ks) {
;     const bf16x8 k0 = *(const bf16x8*)(Kl + lr * kst + ks * 16 + lh * 8);
;     const bf16x8 k1 = *(const bf16x8*)(Kl + (32 + lr) * kst + ks * 16 + lh * 8);
;     s[0] = MFMA32(k0, q[ks], s[0]);
;     s[1] = MFMA32(k1, q[ks], s[1]);
;   }
;   float alpha, psum = 0.f;
;   if (MODE == 0) {
;     float tmax = fmaxf(s[0][0], s[1][0]);
; #pragma unroll
;     for (int i = 1; i < 16; ++i) tmax = fmaxf(tmax, fmaxf(s[0][i], s[1][i]));
;     tmax = fmaxf(tmax, xor32(tmax)) + cbias;
;     if (!ALLON) tmax = lane_on ? tmax : -1e30f;
;     const float mn = fmaxf(m, tmax);
;     alpha = ex2(m - mn);
;     m = mn;
;     const float mc = (ALLON || lane_on) ? mn - cbias : 1e30f;
; #pragma unroll
;     for (int st = 0; st < 2; ++st)
; #pragma unroll
;       for (int i = 0; i < 16; ++i) { const float pe = ex2(s[st][i] - mc); psum += pe; s[st][i] = pe; }
;   } else {
;     float tmax = -1e30f;
; #pragma unroll
;     for (int st = 0; st < 2; ++st)
; #pragma unroll
;       for (int i = 0; i < 16; ++i) {
;         const int key = kbase + st * 32 + 8 * (i >> 2) + 4 * lh + (i & 3);
;         float v;
;         if (MODE == 1) {
;           const int dist = qp - key;
;           const bool ok = (ALLON || lane_on) && dist >= 0 && dist < win;
;           const int di = dist < 0 ? 0 : (dist > 128 ? 128 : dist);
;           v = ok ? s[st][i] + tab[di] : -1e30f;
;         } else {
;           v = (16 * key + 31 <= qp) ? s[st][i] : -1e30f;
;         }
;         s[st][i] = v;
;         tmax = fmaxf(tmax, v);
;       }
;     tmax = fmaxf(tmax, xor32(tmax));
;     const float mn = fmaxf(m, tmax);
;     alpha = ex2(m - mn);
.LBB0_810:
	v_cmp_le_i32_e32 vcc, s6, v138
	v_cmp_ge_i32_e64 s[0:1], s6, v127
	s_and_b64 s[0:1], vcc, s[0:1]
	s_waitcnt lgkmcnt(0)
	s_barrier
	s_and_saveexec_b64 s[28:29], s[0:1]
	s_cbranch_execz .LBB0_807
	v_cmp_gt_i32_e32 vcc, s6, v137
	v_cmp_le_i32_e64 s[0:1], s6, v128
	s_or_b64 s[0:1], vcc, s[0:1]
	s_and_saveexec_b64 s[30:31], s[0:1]
	s_xor_b64 s[0:1], exec, s[30:31]
	s_cbranch_execz .LBB0_880
	v_mov_b32_e32 v0, v195
	v_mov_b32_e32 v63, 0xf149f2ca
	v_and_b32_e32 v1, 31, v0
	v_bfe_u32 v34, v0, 5, 1
	v_mul_u32_u24_e32 v0, 0x48, v1
	v_lshlrev_b32_e32 v33, 1, v0
	v_lshlrev_b32_e32 v0, 4, v34
	v_add3_u32 v32, s25, v33, v0
	ds_read_b128 v[0:3], v32
	ds_read_b128 v[36:39], v32 offset:32
	v_mov_b32_e32 v134, 0xf149f2ca
	s_waitcnt lgkmcnt(1)
	v_mfma_f32_32x32x16_bf16 v[16:31], v[0:3], v[64:67], 0
	ds_read_b128 v[0:3], v32 offset:4608
	s_waitcnt lgkmcnt(1)
	v_mfma_f32_32x32x16_bf16 v[16:31], v[36:39], v[68:71], v[16:31]
	ds_read_b128 v[36:39], v32 offset:4640
	s_waitcnt lgkmcnt(1)
	v_mfma_f32_32x32x16_bf16 v[0:15], v[0:3], v[64:67], 0
	s_waitcnt lgkmcnt(0)
	v_mfma_f32_32x32x16_bf16 v[0:15], v[36:39], v[68:71], v[0:15]
	ds_read_b128 v[36:39], v32 offset:64
	s_waitcnt lgkmcnt(0)
	v_mfma_f32_32x32x16_bf16 v[16:31], v[36:39], v[72:75], v[16:31]
	ds_read_b128 v[36:39], v32 offset:4672
	s_waitcnt lgkmcnt(0)
	v_mfma_f32_32x32x16_bf16 v[0:15], v[36:39], v[72:75], v[0:15]
	ds_read_b128 v[36:39], v32 offset:96
	s_waitcnt lgkmcnt(0)
	v_mfma_f32_32x32x16_bf16 v[16:31], v[36:39], v[76:79], v[16:31]
	ds_read_b128 v[36:39], v32 offset:4704
	v_lshlrev_b32_e32 v32, 2, v34
	v_sub_u32_e32 v32, v129, v32
	v_add_u32_e32 v35, 59, v32
	v_bfe_u32 v245, v195, 6, 2
	v_lshlrev_b32_e32 v245, 12, v245
	v_add_u32_e32 v245, 0x1e014, v245
	v_lshl_add_u32 v244, v35, 2, v245
	s_waitcnt lgkmcnt(0)
	v_mfma_f32_32x32x16_bf16 v[0:15], v[36:39], v[76:79], v[0:15]
	ds_read2_b32 v[196:197], v244 offset0:59 offset1:58
	ds_read2_b32 v[198:199], v244 offset0:57 offset1:56
	ds_read2_b32 v[200:201], v244 offset0:51 offset1:50
	ds_read2_b32 v[202:203], v244 offset0:49 offset1:48
	ds_read2_b32 v[204:205], v244 offset0:43 offset1:42
	ds_read2_b32 v[206:207], v244 offset0:41 offset1:40
	ds_read2_b32 v[208:209], v244 offset0:35 offset1:34
	ds_read2_b32 v[210:211], v244 offset0:33 offset1:32
	ds_read2_b32 v[212:213], v244 offset0:27 offset1:26
	ds_read2_b32 v[214:215], v244 offset0:25 offset1:24
	ds_read2_b32 v[216:217], v244 offset0:19 offset1:18
	ds_read2_b32 v[218:219], v244 offset0:17 offset1:16
	ds_read2_b32 v[236:237], v244 offset0:11 offset1:10
	ds_read2_b32 v[238:239], v244 offset0:9 offset1:8
	ds_read2_b32 v[240:241], v244 offset0:3 offset1:2
	s_waitcnt lgkmcnt(14)
	v_add_f32_e32 v134, v16, v196
	v_add_f32_e32 v63, v17, v197
	ds_read2_b32 v[242:243], v244 offset0:1 offset1:0
	s_waitcnt lgkmcnt(14)
	v_add_f32_e32 v133, v18, v198
	v_add_f32_e32 v58, v19, v199
	s_waitcnt lgkmcnt(13)
	v_add_f32_e32 v132, v20, v200
	v_add_f32_e32 v56, v21, v201
	s_waitcnt lgkmcnt(12)
	v_add_f32_e32 v62, v22, v202
	v_add_f32_e32 v54, v23, v203
	s_waitcnt lgkmcnt(11)
	v_add_f32_e32 v60, v24, v204
	v_add_f32_e32 v51, v25, v205
	s_waitcnt lgkmcnt(10)
	v_add_f32_e32 v57, v26, v206
	v_add_f32_e32 v48, v27, v207
	s_waitcnt lgkmcnt(9)
	v_add_f32_e32 v55, v28, v208
	v_add_f32_e32 v46, v29, v209
	s_waitcnt lgkmcnt(8)
	v_add_f32_e32 v52, v30, v210
	v_add_f32_e32 v43, v31, v211
	s_waitcnt lgkmcnt(7)
	v_add_f32_e32 v49, v0, v212
	v_add_f32_e32 v40, v1, v213
	s_waitcnt lgkmcnt(6)
	v_add_f32_e32 v47, v2, v214
	v_add_f32_e32 v38, v3, v215
	s_waitcnt lgkmcnt(5)
	v_add_f32_e32 v45, v4, v216
	v_add_f32_e32 v37, v5, v217
	s_waitcnt lgkmcnt(4)
	v_add_f32_e32 v42, v6, v218
	v_add_f32_e32 v36, v7, v219
	s_waitcnt lgkmcnt(3)
	v_add_f32_e32 v39, v8, v236
	v_add_f32_e32 v35, v9, v237
	s_waitcnt lgkmcnt(2)
	v_add_f32_e32 v44, v10, v238
	v_add_f32_e32 v41, v11, v239
	s_waitcnt lgkmcnt(1)
	v_add_f32_e32 v53, v12, v240
	v_add_f32_e32 v50, v13, v241
	s_waitcnt lgkmcnt(0)
	v_add_f32_e32 v61, v14, v242
	v_add_f32_e32 v59, v15, v243
	v_max3_f32 v0, v134, s93, v63
	v_max3_f32 v0, v0, v133, v58
	v_max3_f32 v0, v0, v132, v56
	v_max3_f32 v0, v0, v62, v54
	v_max3_f32 v0, v0, v60, v51
	v_max3_f32 v0, v0, v57, v48
	v_max3_f32 v0, v0, v55, v46
	v_max3_f32 v0, v0, v52, v43
	v_max3_f32 v0, v0, v49, v40
	v_max3_f32 v0, v0, v47, v38
	v_max3_f32 v0, v0, v45, v37
	v_max3_f32 v0, v0, v42, v36
	v_max3_f32 v0, v0, v39, v35
	v_max3_f32 v0, v0, v44, v41
	v_max3_f32 v0, v0, v53, v50
	v_max3_f32 v0, v0, v61, v59
	ds_bpermute_b32 v1, v91, v0
	s_waitcnt lgkmcnt(0)
	v_max_f32_e32 v0, v0, v1
	v_add_f32_e32 v1, 0x41000000, v126
	v_cmp_gt_f32_e32 vcc, v0, v1
	s_nop 1
	v_cndmask_b32_e32 v130, v126, v0, vcc
	v_sub_f32_e32 v0, v126, v130
	v_exp_f32_e32 v32, v0
	s_nop 0
	v_cmp_neq_f32_e32 vcc, 1.0, v32
	s_cbranch_vccz .LBB0_883
	v_pk_mul_f32 v[160:161], v[160:161], v[32:33] op_sel_hi:[1,0]
	v_pk_mul_f32 v[162:163], v[162:163], v[32:33] op_sel_hi:[1,0]
	v_pk_mul_f32 v[164:165], v[164:165], v[32:33] op_sel_hi:[1,0]
	v_pk_mul_f32 v[166:167], v[166:167], v[32:33] op_sel_hi:[1,0]
	v_pk_mul_f32 v[168:169], v[168:169], v[32:33] op_sel_hi:[1,0]
	v_pk_mul_f32 v[170:171], v[170:171], v[32:33] op_sel_hi:[1,0]
	v_pk_mul_f32 v[172:173], v[172:173], v[32:33] op_sel_hi:[1,0]
	v_pk_mul_f32 v[174:175], v[174:175], v[32:33] op_sel_hi:[1,0]
	v_pk_mul_f32 v[176:177], v[176:177], v[32:33] op_sel_hi:[1,0]
	v_pk_mul_f32 v[178:179], v[178:179], v[32:33] op_sel_hi:[1,0]
	v_pk_mul_f32 v[180:181], v[180:181], v[32:33] op_sel_hi:[1,0]
	v_pk_mul_f32 v[182:183], v[182:183], v[32:33] op_sel_hi:[1,0]
	v_pk_mul_f32 v[184:185], v[184:185], v[32:33] op_sel_hi:[1,0]
	v_pk_mul_f32 v[186:187], v[186:187], v[32:33] op_sel_hi:[1,0]
	v_pk_mul_f32 v[188:189], v[188:189], v[32:33] op_sel_hi:[1,0]
	v_pk_mul_f32 v[190:191], v[190:191], v[32:33] op_sel_hi:[1,0]
	s_cbranch_execnz .LBB0_879

; #define MFMA32(a, b, c) __builtin_amdgcn_mfma_f32_32x32x16_bf16((a), (b), (c), 0, 0, 0)
; DI float ex2(float x) { return __builtin_amdgcn_exp2f(x); }
; DI float xor32(float v) { return __shfl_xor(v, 32); }
; template <int NDT, int MODE, bool ALLON>
; DI void attn_tile(const bf16_t* Kl, int kst, const bf16_t* Vl, const bf16x8 (&q)[4], f32x16 (&O)[NDT], float& m, float& l,
;                   int kbase, int qp, int win, float cbias, const float* tab, bool lane_on) {
;     ...
;   for (int ks = 0; ks < 4; ++ks) {
;     const bf16x8 k0 = *(const bf16x8*)(Kl + lr * kst + ks * 16 + lh * 8);
;     const bf16x8 k1 = *(const bf16x8*)(Kl + (32 + lr) * kst + ks * 16 + lh * 8);
;     s[0] = MFMA32(k0, q[ks], s[0]);
;     s[1] = MFMA32(k1, q[ks], s[1]);
;   }
;   float alpha, psum = 0.f;
;   if (MODE == 0) {
;     float tmax = fmaxf(s[0][0], s[1][0]);
; #pragma unroll
;     for (int i = 1; i < 16; ++i) tmax = fmaxf(tmax, fmaxf(s[0][i], s[1][i]));
;     tmax = fmaxf(tmax, xor32(tmax)) + cbias;
;     if (!ALLON) tmax = lane_on ? tmax : -1e30f;
;     const float mn = fmaxf(m, tmax);
;     alpha = ex2(m - mn);
;     m = mn;
.LBB0_880:
	s_andn2_saveexec_b64 s[0:1], s[0:1]
	s_cbranch_execz .LBB0_806
	v_mov_b32_e32 v0, v195
	ds_read_b32 v134, v135 offset:37376
	s_nop 0
	v_and_b32_e32 v1, 31, v0
	v_lshrrev_b32_e32 v0, 2, v0
	v_mul_u32_u24_e32 v1, 0x48, v1
	v_and_b32_e32 v133, 8, v0
	v_lshlrev_b32_e32 v132, 1, v1
	v_lshlrev_b32_e32 v0, 1, v133
	v_add3_u32 v4, s25, v132, v0
	ds_read_b128 v[0:3], v4
	s_waitcnt lgkmcnt(0)
	v_mfma_f32_32x32x16_bf16 v[48:63], v[0:3], v[64:67], 0
	ds_read_b128 v[0:3], v4 offset:4608
	s_waitcnt lgkmcnt(0)
	v_mfma_f32_32x32x16_bf16 v[32:47], v[0:3], v[64:67], 0
	ds_read_b128 v[0:3], v4 offset:32
	s_waitcnt lgkmcnt(0)
	v_mfma_f32_32x32x16_bf16 v[48:63], v[0:3], v[68:71], v[48:63]
	ds_read_b128 v[0:3], v4 offset:4640
	s_waitcnt lgkmcnt(0)
	v_mfma_f32_32x32x16_bf16 v[32:47], v[0:3], v[68:71], v[32:47]
	ds_read_b128 v[0:3], v4 offset:64
	s_waitcnt lgkmcnt(0)
	v_mfma_f32_32x32x16_bf16 v[48:63], v[0:3], v[72:75], v[48:63]
	ds_read_b128 v[0:3], v4 offset:4672
	s_waitcnt lgkmcnt(0)
	v_mfma_f32_32x32x16_bf16 v[32:47], v[0:3], v[72:75], v[32:47]
	ds_read_b128 v[0:3], v4 offset:4704
	s_waitcnt lgkmcnt(0)
	v_mfma_f32_32x32x16_bf16 v[32:47], v[0:3], v[76:79], v[32:47]
	ds_read_b128 v[0:3], v4 offset:96
	s_waitcnt lgkmcnt(0)
	v_mfma_f32_32x32x16_bf16 v[48:63], v[0:3], v[76:79], v[48:63]
	s_nop 8
	v_max3_f32 v0, v32, v33, v34
	v_max3_f32 v0, v0, v35, v36
	v_max3_f32 v0, v0, v37, v38
	v_max3_f32 v0, v0, v39, v40
	v_max3_f32 v0, v0, v41, v42
	v_max3_f32 v0, v0, v43, v44
	v_max3_f32 v0, v0, v45, v46
	v_max_f32_e32 v0, v0, v47
	v_max3_f32 v1, v48, v49, v50
	v_max3_f32 v1, v1, v51, v52
	v_max3_f32 v1, v1, v53, v54
	v_max3_f32 v1, v1, v55, v56
	v_max3_f32 v1, v1, v57, v58
	v_max3_f32 v1, v1, v59, v60
	v_max3_f32 v1, v1, v61, v62
	v_max_f32_e32 v1, v1, v63
	v_max_f32_e32 v0, v0, v1
	ds_bpermute_b32 v1, v91, v0
	s_waitcnt lgkmcnt(0)
	v_max_f32_e32 v1, v1, v1
	v_max_f32_e32 v0, v0, v1
	v_add_f32_e32 v0, v134, v0
	v_add_f32_e32 v1, 0x41000000, v126
	v_cmp_gt_f32_e32 vcc, v0, v1
	s_nop 1
	v_cndmask_b32_e32 v130, v126, v0, vcc
	v_sub_f32_e32 v0, v126, v130
	v_exp_f32_e32 v126, v0
	s_nop 0
	v_cmp_neq_f32_e32 vcc, 1.0, v126
	s_cbranch_vccz .LBB0_884
	v_pk_mul_f32 v[160:161], v[160:161], v[126:127] op_sel_hi:[1,0]
	v_pk_mul_f32 v[162:163], v[162:163], v[126:127] op_sel_hi:[1,0]
	v_pk_mul_f32 v[164:165], v[164:165], v[126:127] op_sel_hi:[1,0]
	v_pk_mul_f32 v[166:167], v[166:167], v[126:127] op_sel_hi:[1,0]
	v_pk_mul_f32 v[168:169], v[168:169], v[126:127] op_sel_hi:[1,0]
	v_pk_mul_f32 v[170:171], v[170:171], v[126:127] op_sel_hi:[1,0]
	v_pk_mul_f32 v[172:173], v[172:173], v[126:127] op_sel_hi:[1,0]
	v_pk_mul_f32 v[174:175], v[174:175], v[126:127] op_sel_hi:[1,0]
	v_pk_mul_f32 v[176:177], v[176:177], v[126:127] op_sel_hi:[1,0]
	v_pk_mul_f32 v[178:179], v[178:179], v[126:127] op_sel_hi:[1,0]
	v_pk_mul_f32 v[180:181], v[180:181], v[126:127] op_sel_hi:[1,0]
	v_pk_mul_f32 v[182:183], v[182:183], v[126:127] op_sel_hi:[1,0]
	v_pk_mul_f32 v[184:185], v[184:185], v[126:127] op_sel_hi:[1,0]
	v_pk_mul_f32 v[186:187], v[186:187], v[126:127] op_sel_hi:[1,0]
	v_pk_mul_f32 v[188:189], v[188:189], v[126:127] op_sel_hi:[1,0]
	v_pk_mul_f32 v[190:191], v[190:191], v[126:127] op_sel_hi:[1,0]
	s_cbranch_execnz .LBB0_805
	s_branch .LBB0_804

; DI void task_attnB(const P& p, int layer, int task, bf16_t* sm, int dm) {
;     ...
;   float* tabs = (float*)((unsigned char*)sm + 36864);
;   __syncthreads();
;   for (int i = tid; i < 4 * 129; i += NTHR) {
;     const int r = i / 129, d = i % 129;
;     tabs[r * 132 + d] = ((const float*)(p.ws + O_TABS))[(4 + g * 4 + r) * 132 + d];
;   }
.LBB0_886:
	s_and_b64 vcc, exec, s[0:1]
	s_cbranch_vccz .LBB0_970
	v_mov_b32_e32 v0, v195
	s_and_b32 s6, s34, 1
	s_movk_i32 s0, 0x204
	s_lshl_b32 s7, s6, 2
	v_cmp_gt_i32_e32 vcc, s0, v0
	s_barrier
	s_mul_i32 s100, s6, 0x840
	s_addk_i32 s100, 0x840
	s_add_u32 s36, s20, s100
	s_addc_u32 s37, s21, 0
	s_movk_i32 s100, 0x80
	s_movk_i32 s101, 0x80
	v_subrev_u32_e32 v247, 64, v195
	v_med3_i32 v249, v247, 0, s100
	v_lshlrev_b32_e32 v249, 2, v249
	global_load_dword v196, v249, s[36:37]
	global_load_dword v197, v249, s[36:37] offset:528
	global_load_dword v198, v249, s[36:37] offset:1056
	global_load_dword v199, v249, s[36:37] offset:1584
	s_and_saveexec_b64 s[0:1], vcc
	s_cbranch_execz .LBB0_895
	v_max_i32_e32 v1, 4, v0
	v_sub_u32_e32 v1, v1, v0
	v_add_u32_e32 v2, 0x1ff, v1
	s_movk_i32 s2, 0x1ff
	v_cmp_lt_u32_e32 vcc, s2, v2
	s_mov_b64 s[4:5], -1
	v_mov_b32_e32 v1, v0
	s_and_saveexec_b64 s[2:3], vcc
	s_cbranch_execz .LBB0_892
	v_lshrrev_b32_e32 v1, 9, v2
	v_add_u32_e32 v4, 1, v1
	s_add_i32 s8, s7, 4
	v_and_b32_e32 v5, 0xfffffe, v4
	v_add_u32_e32 v1, 0x200, v0
	s_mov_b32 s9, s8
	s_mov_b64 s[4:5], 0
	v_mov_b32_e32 v6, v5
	v_mov_b64_e32 v[2:3], v[0:1]

; DI int tidx() { int t = threadIdx.x; asm volatile("" : "+v"(t)); return t; }
; DI void task_attnB(const P& p, int layer, int task, bf16_t* sm, int dm) {
;   const int tid = tidx(), lane = tid & 63, wv = tid >> 6, hr = wv & 3, qs = wv >> 2;
;   const int lr = lane & 31, lh = lane >> 5;
;   const int qb = 63 - (task >> 3), bg = task & 7, b = bg >> 1, g = bg & 1, head = g * 4 + hr;
;   float* tabs = (float*)((unsigned char*)sm + 36864);
;   __syncthreads();
;   for (int i = tid; i < 4 * 129; i += NTHR) {
;     const int r = i / 129, d = i % 129;
;     tabs[r * 132 + d] = ((const float*)(p.ws + O_TABS))[(4 + g * 4 + r) * 132 + d];
;   }
;   const int q0 = qb * 64, qmin = q0 + qs * 32, qp = qmin + lr;
;   bf16_t* bq = (bf16_t*)(p.ws + O_BQ);
;   bf16x8 q[4];
;   {
;     const bf16_t* qptr = bq + (size_t)(b * S_ + qp) * 512 + head * 64 + lh * 8;
; #pragma unroll
;     for (int ks = 0; ks < 4; ++ks) q[ks] = *(const bf16x8*)(qptr + ks * 16);
;   }
;   f32x16 O[2];
; #pragma unroll
;   for (int dt = 0; dt < 2; ++dt)
; #pragma unroll
;     for (int i = 0; i < 16; ++i) O[dt][i] = 0.f;
;   float m = p.sinks[layer * 8 + head] * LOG2E, l = lh == 0 ? 1.f : 0.f;
;   const bf16_t* kg = (const bf16_t*)(p.ws + O_BK) + (size_t)b * S_ * 128 + g * 64;
;   const bf16_t* vg = (const bf16_t*)(p.ws + O_BVT) + (size_t)((b * 2 + g) * 64) * S_;
;   const int kt_lo = q0 >= 127 ? (q0 - 127) >> 6 : 0, kt_hi = qb;
;   KVRegs R;
;   kv_gload(R, kg, 128, vg, S_, kt_lo * 64);
.LBB0_895:
	s_or_b64 exec, exec, s[0:1]
	v_mov_b32_e32 v246, 0xf149f2ca
	v_lshlrev_b32_e32 v244, 2, v195
	v_add_u32_e32 v244, 0x1e000, v244
	s_waitcnt vmcnt(0)
	v_cmp_gt_u32_e64 s[98:99], s101, v247
	s_nop 1
	v_cndmask_b32_e64 v196, v246, v196, s[98:99]
	v_cndmask_b32_e64 v197, v246, v197, s[98:99]
	v_cndmask_b32_e64 v198, v246, v198, s[98:99]
	v_cndmask_b32_e64 v199, v246, v199, s[98:99]
	ds_write_b32 v244, v196
	ds_write_b32 v244, v197 offset:4096
	ds_write_b32 v244, v198 offset:8192
	ds_write_b32 v244, v199 offset:12288
	s_add_i32 s1, s34, 0xfffffbf0
	s_lshr_b32 s0, s1, 3
	v_bfe_u32 v2, v0, 6, 2
	v_and_b32_e32 v1, 31, v0
	v_bfe_u32 v91, v0, 5, 1
	s_xor_b32 s25, s0, 63
	v_ashrrev_i32_e32 v0, 3, v0
	s_lshl_b32 s0, s25, 6
	v_and_b32_e32 v3, 0xffffffe0, v0
	v_add_u32_e32 v0, s0, v3
	s_bfe_u32 s2, s34, 0x20001
	v_or_b32_e32 v92, v0, v1
	v_lshl_add_u32 v4, s2, 12, v92
	v_ashrrev_i32_e32 v5, 31, v4
	v_or_b32_e32 v6, s7, v2
	v_lshlrev_b64 v[4:5], 10, v[4:5]
	v_lshl_add_u64 v[4:5], s[52:53], 0, v[4:5]
	v_lshlrev_b32_e32 v192, 7, v6
	v_lshl_add_u64 v[56:57], v[4:5], 0, v[192:193]
	v_lshlrev_b32_e32 v192, 4, v91
	v_lshl_add_u64 v[4:5], v[56:57], 0, v[192:193]
	v_readlane_b32 s3, v255, 15
	v_readlane_b32 s36, v253, 6
	global_load_dwordx4 v[32:35], v[4:5], off
	global_load_dwordx4 v[36:39], v[4:5], off offset:32
	global_load_dwordx4 v[40:43], v[4:5], off offset:64
	global_load_dwordx4 v[44:47], v[4:5], off offset:96
	v_or_b32_e32 v192, s3, v6
	v_readlane_b32 s46, v253, 16
	v_readlane_b32 s47, v253, 17
	s_add_i32 s3, s0, 0xffffff81
	s_ashr_i32 s3, s3, 6
	v_lshl_add_u64 v[4:5], v[192:193], 2, s[46:47]
	global_load_dword v4, v[4:5], off
	s_cmp_gt_u32 s25, 1
	v_cmp_eq_u32_e32 vcc, 0, v91
	s_cselect_b32 s30, s3, 0
	v_mov_b32_e32 v59, 0
	v_cndmask_b32_e64 v98, 0, 1.0, vcc
	v_mov_b32_e32 v5, v195
	s_cmp_le_i32 s30, s25
	v_readlane_b32 s37, v253, 7
	v_readlane_b32 s38, v253, 8
	v_readlane_b32 s39, v253, 9
	v_readlane_b32 s40, v253, 10
	v_readlane_b32 s41, v253, 11
	v_readlane_b32 s42, v253, 12
	v_readlane_b32 s43, v253, 13
	v_readlane_b32 s44, v253, 14
	v_readlane_b32 s45, v253, 15
	v_readlane_b32 s48, v253, 18
	v_readlane_b32 s49, v253, 19
	v_readlane_b32 s50, v253, 20
	v_readlane_b32 s51, v253, 21
	s_cbranch_scc0 .LBB0_1075
	s_lshl_b32 s2, s2, 20
	v_readlane_b32 s4, v253, 48
	v_readlane_b32 s5, v253, 49
	s_add_u32 s2, s4, s2
	s_addc_u32 s3, s5, 0
	s_lshl_b32 s4, s6, 7
	s_add_u32 s2, s2, s4
	s_addc_u32 s3, s3, 0
	s_lshl_b32 s1, s1, 19
	s_and_b32 s1, s1, 0x380000
	v_readlane_b32 s4, v253, 46
	v_readlane_b32 s5, v253, 47
	s_add_u32 s4, s4, s1
	v_ashrrev_i32_e32 v6, 3, v5
	s_addc_u32 s5, s5, 0
	v_ashrrev_i32_e32 v7, 31, v6
	s_lshl_b32 s6, s30, 6
	v_lshlrev_b64 v[8:9], 13, v[6:7]
	v_add_u32_e32 v6, s6, v6
	v_lshl_add_u64 v[8:9], s[4:5], 0, v[8:9]
	s_ashr_i32 s7, s6, 31
	v_lshlrev_b32_e32 v5, 4, v5
	v_ashrrev_i32_e32 v7, 31, v6
	v_lshl_add_u64 v[8:9], s[6:7], 1, v[8:9]
	v_and_b32_e32 v192, 0x70, v5
	v_lshlrev_b64 v[6:7], 8, v[6:7]
	v_lshl_add_u64 v[8:9], v[8:9], 0, v[192:193]
	v_lshl_add_u64 v[6:7], s[2:3], 0, v[6:7]
	v_lshl_add_u64 v[6:7], v[6:7], 0, v[192:193]
	global_load_dwordx4 v[52:55], v[8:9], off
	global_load_dwordx4 v[48:51], v[6:7], off
	v_add_u32_e32 v93, 0xffffff42, v0
	v_or_b32_e32 v94, 31, v0
	v_add_u32_e32 v0, v0, v1
	s_sub_i32 s0, s0, 59
	v_subrev_u32_e32 v0, s6, v0
	s_waitcnt vmcnt(2)
	v_mul_f32_e32 v90, 0x3fb8aa3b, v4
	v_mul_u32_u24_e32 v4, 0x210, v2
	v_mad_u32_u24 v95, v2, s92, 0
	v_add3_u32 v2, s0, v3, v1
	v_lshlrev_b32_e32 v0, 2, v0
	v_readlane_b32 s0, v255, 4
	v_mov_b32_e32 v86, 0
	v_subrev_u32_e32 v96, s6, v2
	v_add3_u32 v97, v4, v0, s0
	v_mov_b32_e32 v87, v86
	v_mov_b32_e32 v88, v86
	v_mov_b32_e32 v89, v86
	v_mov_b32_e32 v84, v86
	v_mov_b32_e32 v85, v86
	v_mov_b32_e32 v82, v86
	v_mov_b32_e32 v83, v86
	v_mov_b32_e32 v80, v86
	v_mov_b32_e32 v81, v86
	v_mov_b32_e32 v76, v86
	v_mov_b32_e32 v77, v86
	v_mov_b32_e32 v72, v86
	v_mov_b32_e32 v73, v86
	v_mov_b32_e32 v68, v86
	v_mov_b32_e32 v69, v86
	v_mov_b32_e32 v78, v86
	v_mov_b32_e32 v79, v86
	v_mov_b32_e32 v74, v86
	v_mov_b32_e32 v75, v86
	v_mov_b32_e32 v70, v86
	v_mov_b32_e32 v71, v86
	v_mov_b32_e32 v66, v86
	v_mov_b32_e32 v67, v86
	v_mov_b32_e32 v64, v86
	v_mov_b32_e32 v65, v86
	v_mov_b32_e32 v62, v86
	v_mov_b32_e32 v63, v86
	v_mov_b32_e32 v60, v86
	v_mov_b32_e32 v61, v86
	v_mov_b32_e32 v58, v86
	v_mov_b32_e32 v59, v86
	s_branch .LBB0_900

; template <int NDT, int MODE, bool ALLON>
; DI void attn_tile(const bf16_t* Kl, int kst, const bf16_t* Vl, const bf16x8 (&q)[4], f32x16 (&O)[NDT], float& m, float& l,
;                   int kbase, int qp, int win, float cbias, const float* tab, bool lane_on) {
;     ...
;   for (int ks = 0; ks < 4; ++ks) {
;     const bf16x8 k0 = *(const bf16x8*)(Kl + lr * kst + ks * 16 + lh * 8);
;     const bf16x8 k1 = *(const bf16x8*)(Kl + (32 + lr) * kst + ks * 16 + lh * 8);
;     s[0] = MFMA32(k0, q[ks], s[0]);
;     s[1] = MFMA32(k1, q[ks], s[1]);
;   }
;   float alpha, psum = 0.f;
;   if (MODE == 0) {
;     float tmax = fmaxf(s[0][0], s[1][0]);
; #pragma unroll
;     for (int i = 1; i < 16; ++i) tmax = fmaxf(tmax, fmaxf(s[0][i], s[1][i]));
;     tmax = fmaxf(tmax, xor32(tmax)) + cbias;
;     if (!ALLON) tmax = lane_on ? tmax : -1e30f;
;     const float mn = fmaxf(m, tmax);
;     alpha = ex2(m - mn);
;     m = mn;
;     const float mc = (ALLON || lane_on) ? mn - cbias : 1e30f;
; #pragma unroll
;     for (int st = 0; st < 2; ++st)
; #pragma unroll
;       for (int i = 0; i < 16; ++i) { const float pe = ex2(s[st][i] - mc); psum += pe; s[st][i] = pe; }
;   } else {
;     float tmax = -1e30f;
; #pragma unroll
;     for (int st = 0; st < 2; ++st)
; #pragma unroll
;       for (int i = 0; i < 16; ++i) {
;         const int key = kbase + st * 32 + 8 * (i >> 2) + 4 * lh + (i & 3);
;         float v;
;         if (MODE == 1) {
;           const int dist = qp - key;
;           const bool ok = (ALLON || lane_on) && dist >= 0 && dist < win;
;           const int di = dist < 0 ? 0 : (dist > 128 ? 128 : dist);
;           v = ok ? s[st][i] + tab[di] : -1e30f;
;         } else {
;           v = (16 * key + 31 <= qp) ? s[st][i] : -1e30f;
;         }
;         s[st][i] = v;
;         tmax = fmaxf(tmax, v);
;       }
;     tmax = fmaxf(tmax, xor32(tmax));
;     const float mn = fmaxf(m, tmax);
;     alpha = ex2(m - mn);
;     m = mn;
; #pragma unroll
;     for (int st = 0; st < 2; ++st)
; #pragma unroll
;       for (int i = 0; i < 16; ++i) {
;         const float pe = s[st][i] > -5e29f ? ex2(s[st][i] - mn) : 0.f;
;         psum += pe;
;         s[st][i] = pe;
;       }
;   }
;   l = l * alpha + psum;
;   if (__ballot(alpha != 1.f)) {
; #pragma unroll
;     for (int dt = 0; dt < NDT; ++dt)
; #pragma unroll
;       for (int i = 0; i < 16; ++i) O[dt][i] *= alpha;
;   }
.LBB0_902:
	v_cmp_le_i32_e32 vcc, s6, v94
	v_cmp_ge_i32_e64 s[0:1], s6, v93
	s_and_b64 s[28:29], vcc, s[0:1]
	s_waitcnt lgkmcnt(0)
	s_barrier
	s_and_saveexec_b64 s[0:1], s[28:29]
	s_cbranch_execz .LBB0_899
	v_mov_b32_e32 v0, v195
	v_mov_b32_e32 v131, 0xf149f2ca
	v_and_b32_e32 v1, 31, v0
	v_bfe_u32 v108, v0, 5, 1
	v_mul_u32_u24_e32 v0, 0x48, v1
	v_lshlrev_b32_e32 v99, 1, v0
	v_lshlrev_b32_e32 v109, 4, v108
	v_add3_u32 v110, s31, v99, v109
	ds_read_b128 v[0:3], v110 offset:4608
	ds_read_b128 v[4:7], v110
	ds_read_b128 v[100:103], v110 offset:32
	ds_read_b128 v[104:107], v110 offset:4640
	s_waitcnt lgkmcnt(2)
	v_mfma_f32_32x32x16_bf16 v[16:31], v[4:7], v[32:35], 0
	v_mov_b32_e32 v133, 0xf149f2ca
	v_mfma_f32_32x32x16_bf16 v[0:15], v[0:3], v[32:35], 0
	s_waitcnt lgkmcnt(1)
	v_mfma_f32_32x32x16_bf16 v[16:31], v[100:103], v[36:39], v[16:31]
	s_waitcnt lgkmcnt(0)
	v_mfma_f32_32x32x16_bf16 v[0:15], v[104:107], v[36:39], v[0:15]
	ds_read_b128 v[100:103], v110 offset:64
	ds_read_b128 v[104:107], v110 offset:4672
	s_waitcnt lgkmcnt(1)
	v_mfma_f32_32x32x16_bf16 v[16:31], v[100:103], v[40:43], v[16:31]
	s_waitcnt lgkmcnt(0)
	v_mfma_f32_32x32x16_bf16 v[0:15], v[104:107], v[40:43], v[0:15]
	ds_read_b128 v[100:103], v110 offset:96
	ds_read_b128 v[104:107], v110 offset:4704
	s_waitcnt lgkmcnt(1)
	v_mfma_f32_32x32x16_bf16 v[16:31], v[100:103], v[44:47], v[16:31]
	v_lshlrev_b32_e32 v100, 2, v108
	v_sub_u32_e32 v134, v96, v100
	v_add_u32_e32 v101, 59, v134
	v_bfe_u32 v245, v195, 6, 2
	v_lshlrev_b32_e32 v245, 12, v245
	v_add_u32_e32 v245, 0x1e014, v245
	v_lshl_add_u32 v244, v101, 2, v245
	v_sub_u32_e32 v101, v97, v109
	s_waitcnt lgkmcnt(0)
	v_mfma_f32_32x32x16_bf16 v[0:15], v[104:107], v[44:47], v[0:15]
	ds_read2_b32 v[196:197], v244 offset0:59 offset1:58
	ds_read2_b32 v[198:199], v244 offset0:57 offset1:56
	ds_read2_b32 v[200:201], v244 offset0:51 offset1:50
	ds_read2_b32 v[202:203], v244 offset0:49 offset1:48
	ds_read2_b32 v[204:205], v244 offset0:43 offset1:42
	ds_read2_b32 v[206:207], v244 offset0:41 offset1:40
	ds_read2_b32 v[208:209], v244 offset0:35 offset1:34
	ds_read2_b32 v[210:211], v244 offset0:33 offset1:32
	ds_read2_b32 v[212:213], v244 offset0:27 offset1:26
	ds_read2_b32 v[214:215], v244 offset0:25 offset1:24
	ds_read2_b32 v[216:217], v244 offset0:19 offset1:18
	ds_read2_b32 v[218:219], v244 offset0:17 offset1:16
	ds_read2_b32 v[236:237], v244 offset0:11 offset1:10
	ds_read2_b32 v[238:239], v244 offset0:9 offset1:8
	ds_read2_b32 v[240:241], v244 offset0:3 offset1:2
	s_waitcnt lgkmcnt(14)
	v_add_f32_e32 v133, v16, v196
	v_add_f32_e32 v131, v17, v197
	ds_read2_b32 v[242:243], v244 offset0:1 offset1:0
	s_waitcnt lgkmcnt(14)
	v_add_f32_e32 v132, v18, v198
	v_add_f32_e32 v128, v19, v199
	s_waitcnt lgkmcnt(13)
	v_add_f32_e32 v130, v20, v200
	v_add_f32_e32 v126, v21, v201
	s_waitcnt lgkmcnt(12)
	v_add_f32_e32 v129, v22, v202
	v_add_f32_e32 v124, v23, v203
	s_waitcnt lgkmcnt(11)
	v_add_f32_e32 v127, v24, v204
	v_add_f32_e32 v122, v25, v205
	s_waitcnt lgkmcnt(10)
	v_add_f32_e32 v125, v26, v206
	v_add_f32_e32 v120, v27, v207
	s_waitcnt lgkmcnt(9)
	v_add_f32_e32 v123, v28, v208
	v_add_f32_e32 v116, v29, v209
	s_waitcnt lgkmcnt(8)
	v_add_f32_e32 v121, v30, v210
	v_add_f32_e32 v114, v31, v211
	s_waitcnt lgkmcnt(7)
	v_add_f32_e32 v118, v0, v212
	v_add_f32_e32 v110, v1, v213
	s_waitcnt lgkmcnt(6)
	v_add_f32_e32 v115, v2, v214
	v_add_f32_e32 v108, v3, v215
	s_waitcnt lgkmcnt(5)
	v_add_f32_e32 v112, v4, v216
	v_add_f32_e32 v104, v5, v217
	s_waitcnt lgkmcnt(4)
	v_add_f32_e32 v109, v6, v218
	v_add_f32_e32 v103, v7, v219
	s_waitcnt lgkmcnt(3)
	v_add_f32_e32 v105, v8, v236
	v_add_f32_e32 v102, v9, v237
	s_waitcnt lgkmcnt(2)
	v_add_f32_e32 v107, v10, v238
	v_add_f32_e32 v106, v11, v239
	s_waitcnt lgkmcnt(1)
	v_add_f32_e32 v113, v12, v240
	v_add_f32_e32 v111, v13, v241
	s_waitcnt lgkmcnt(0)
	v_add_f32_e32 v119, v14, v242
	v_add_f32_e32 v117, v15, v243
	v_max3_f32 v0, v133, s93, v131
	v_max3_f32 v0, v0, v132, v128
	v_max3_f32 v0, v0, v130, v126
	v_max3_f32 v0, v0, v129, v124
	v_max3_f32 v0, v0, v127, v122
	v_max3_f32 v0, v0, v125, v120
	v_max3_f32 v0, v0, v123, v116
	v_max3_f32 v0, v0, v121, v114
	v_max3_f32 v0, v0, v118, v110
	v_max3_f32 v0, v0, v115, v108
	v_max3_f32 v0, v0, v112, v104
	v_max3_f32 v0, v0, v109, v103
	v_and_b32_e32 v2, 64, v231
	v_max3_f32 v0, v0, v105, v102
	v_xor_b32_e32 v1, 32, v231
	v_add_u32_e32 v2, 64, v2
	v_max3_f32 v0, v0, v107, v106
	v_cmp_lt_i32_e32 vcc, v1, v2
	v_max3_f32 v0, v0, v113, v111
	v_max3_f32 v0, v0, v119, v117
	v_cndmask_b32_e32 v1, v231, v1, vcc
	v_lshlrev_b32_e32 v1, 2, v1
	ds_bpermute_b32 v1, v1, v0
	s_waitcnt lgkmcnt(0)
	v_max_f32_e32 v0, v0, v1
	v_add_f32_e32 v1, 0x41000000, v90
	v_cmp_gt_f32_e32 vcc, v0, v1
	s_nop 1
	v_cndmask_b32_e32 v101, v90, v0, vcc
	v_sub_f32_e32 v0, v90, v101
	v_exp_f32_e32 v90, v0
	s_nop 0
	v_cmp_neq_f32_e32 vcc, 1.0, v90
	s_cbranch_vccz .LBB0_969
	v_pk_mul_f32 v[0:1], v[86:87], v[90:91] op_sel_hi:[1,0]
	v_pk_mul_f32 v[2:3], v[88:89], v[90:91] op_sel_hi:[1,0]
	v_pk_mul_f32 v[4:5], v[84:85], v[90:91] op_sel_hi:[1,0]
	v_pk_mul_f32 v[6:7], v[82:83], v[90:91] op_sel_hi:[1,0]
	v_pk_mul_f32 v[8:9], v[80:81], v[90:91] op_sel_hi:[1,0]
	v_pk_mul_f32 v[10:11], v[76:77], v[90:91] op_sel_hi:[1,0]
	v_pk_mul_f32 v[12:13], v[72:73], v[90:91] op_sel_hi:[1,0]
	v_pk_mul_f32 v[14:15], v[68:69], v[90:91] op_sel_hi:[1,0]
	v_pk_mul_f32 v[16:17], v[78:79], v[90:91] op_sel_hi:[1,0]
	v_pk_mul_f32 v[18:19], v[74:75], v[90:91] op_sel_hi:[1,0]
	v_pk_mul_f32 v[20:21], v[70:71], v[90:91] op_sel_hi:[1,0]
	v_pk_mul_f32 v[22:23], v[66:67], v[90:91] op_sel_hi:[1,0]
	v_pk_mul_f32 v[24:25], v[64:65], v[90:91] op_sel_hi:[1,0]
	v_pk_mul_f32 v[26:27], v[62:63], v[90:91] op_sel_hi:[1,0]
	v_pk_mul_f32 v[28:29], v[60:61], v[90:91] op_sel_hi:[1,0]
	v_pk_mul_f32 v[30:31], v[58:59], v[90:91] op_sel_hi:[1,0]
	s_cbranch_execnz .LBB0_898
	s_branch .LBB0_897

; DI int tidx() { int t = threadIdx.x; asm volatile("" : "+v"(t)); return t; }
; DI void task_attnA(const P& p, int layer, int task, bf16_t* sm, int dm) {
;   const int tid = tidx(), lane = tid & 63, wv = tid >> 6, c = wv & 1, qs = wv >> 1;
;   const int lr = lane & 31, lh = lane >> 5;
;   const int qb = 31 - (task >> 4), bh = task & 15, b = bh >> 2, h = bh & 3;
;   float* tab = (float*)((unsigned char*)sm + 71680);
;   bf16x8* qlds = (bf16x8*)((unsigned char*)sm + 72704) + wv * 256 + lane;
;   float* xbuf = (float*)((unsigned char*)sm);
;   __syncthreads();
;   if (tid < 129) tab[tid] = ((const float*)(p.ws + O_TABS))[h * 132 + tid];
;   const int q0 = qb * 128, qmin = q0 + qs * 32, qp = qmin + lr;
;   bf16_t* aq = (bf16_t*)(p.ws + O_AQ);
;   {
;     const bf16_t* qptr = aq + (size_t)(b * S_ + qp) * 512 + h * 128 + c * 64 + lh * 8;
; #pragma unroll
;     for (int ks = 0; ks < 4; ++ks) qlds[ks * 64] = *(const bf16x8*)(qptr + ks * 16);
;   }
;   f32x16 O[4];
; #pragma unroll
;   for (int dt = 0; dt < 4; ++dt)
; #pragma unroll
;     for (int i = 0; i < 16; ++i) O[dt][i] = 0.f;
;   float m = -1e30f, l = 0.f;
;   const bf16_t* kg = (const bf16_t*)(p.ws + O_AK) + (size_t)b * S_ * 512 + h * 128;
;   const bf16_t* vg = (const bf16_t*)(p.ws + O_AVT) + (size_t)((b * 4 + h) * 128) * S_;
;   u32x4 rk0, rk1, rv0, rv1;
;     ...
;   const int kt_hi = 2 * qb + 1;
;   A_GLOAD(0, 0) A_GLOAD(1, 0)
.LBB0_972:
	v_mov_b32_e32 v138, v195
	s_movk_i32 s0, 0x81
	s_and_b32 s2, s34, 3
	v_cmp_gt_i32_e32 vcc, s0, v138
	s_barrier
	s_mul_i32 s100, s2, 0x210
	s_add_u32 s36, s20, s100
	s_addc_u32 s37, s21, 0
	s_movk_i32 s100, 0x80
	s_mov_b32 s101, 0x40000000
	v_subrev_u32_e32 v247, 64, v195
	v_med3_i32 v249, v247, 0, s100
	v_lshlrev_b32_e32 v249, 2, v249
	global_load_dword v196, v249, s[36:37]
	s_and_saveexec_b64 s[0:1], vcc
	s_cbranch_execz .LBB0_974
	s_mul_i32 s3, s2, 0x84
	v_add_u32_e32 v0, s3, v138
	v_ashrrev_i32_e32 v1, 31, v0
	v_lshl_add_u64 v[0:1], v[0:1], 2, s[20:21]
	global_load_dword v0, v[0:1], off
	v_lshl_add_u32 v1, v138, 2, 0
	v_add_u32_e32 v1, 0x11800, v1
	s_waitcnt vmcnt(0)
	ds_write_b32 v1, v0
.LBB0_974:
	s_or_b64 exec, exec, s[0:1]
	v_mov_b32_e32 v246, 0xf149f2ca
	v_lshlrev_b32_e32 v244, 2, v195
	v_add_u32_e32 v244, 0x1e000, v244
	s_waitcnt vmcnt(0)
	v_cmp_gt_u32_e64 s[98:99], s101, v247
	s_nop 1
	v_cndmask_b32_e64 v196, v246, v196, s[98:99]
	ds_write_b32 v244, v196
	s_add_i32 s3, s34, -16
	s_lshr_b32 s0, s3, 4
	s_xor_b32 s4, s0, 31
	v_ashrrev_i32_e32 v0, 2, v138
	s_lshl_b32 s5, s4, 7
	v_and_b32_e32 v27, 0xffffffe0, v0
	v_and_b32_e32 v139, 31, v138
	v_add_u32_e32 v28, s5, v27
	s_bfe_u32 s0, s34, 0x20002
	v_or_b32_e32 v0, v28, v139
	v_lshl_add_u32 v0, s0, 12, v0
	s_lshl_b32 s66, s2, 8
	s_lshl_b32 s0, s0, 22
	s_add_u32 s0, s56, s0
	v_ashrrev_i32_e32 v16, 4, v138
	s_addc_u32 s1, s57, 0
	v_ashrrev_i32_e32 v17, 31, v16
	s_add_u32 s0, s0, s66
	v_lshlrev_b64 v[18:19], 10, v[16:17]
	v_lshlrev_b32_e32 v17, 3, v138
	s_addc_u32 s1, s1, 0
	s_lshl_b32 s2, s3, 20
	v_and_b32_e32 v20, 0x78, v17
	s_and_b32 s2, s2, 0xf00000
	v_readlane_b32 s6, v253, 50
	v_lshlrev_b32_e32 v126, 1, v20
	v_ashrrev_i32_e32 v20, 3, v138
	v_readlane_b32 s7, v253, 51
	s_add_u32 s2, s6, s2
	v_ashrrev_i32_e32 v21, 31, v20
	v_ashrrev_i32_e32 v1, 31, v0
	s_addc_u32 s3, s7, 0
	v_lshlrev_b64 v[22:23], 13, v[20:21]
	v_and_b32_e32 v17, 56, v17
	v_ashrrev_i32_e32 v26, 6, v138
	v_lshlrev_b64 v[0:1], 10, v[0:1]
	v_lshl_add_u64 v[22:23], s[2:3], 0, v[22:23]
	v_lshlrev_b32_e32 v128, 1, v17
	v_mov_b32_e32 v129, v193
	v_add_u32_e32 v17, 0x200, v138
	v_and_b32_e32 v140, 1, v26
	v_lshl_add_u64 v[0:1], s[58:59], 0, v[0:1]
	v_lshl_add_u64 v[130:131], v[22:23], 0, v[128:129]
	v_ashrrev_i32_e32 v22, 4, v17
	v_bfe_u32 v137, v138, 5, 1
	v_lshl_add_u64 v[124:125], v[0:1], 0, s[66:67]
	v_lshlrev_b32_e32 v192, 7, v140
	v_ashrrev_i32_e32 v23, 31, v22
	v_lshl_add_u64 v[0:1], v[124:125], 0, v[192:193]
	v_lshlrev_b32_e32 v192, 4, v137
	v_lshl_add_u64 v[18:19], s[0:1], 0, v[18:19]
	v_mov_b32_e32 v127, v193
	v_lshlrev_b64 v[24:25], 10, v[22:23]
	v_lshl_add_u64 v[12:13], v[0:1], 0, v[192:193]
	v_lshl_add_u64 v[18:19], v[18:19], 0, v[126:127]
	v_lshl_add_u64 v[24:25], s[0:1], 0, v[24:25]
	global_load_dwordx4 v[0:3], v[12:13], off
	global_load_dwordx4 v[4:7], v[12:13], off offset:32
	global_load_dwordx4 v[8:11], v[12:13], off offset:64
	s_nop 0
	global_load_dwordx4 v[12:15], v[12:13], off offset:96
	v_lshl_add_u64 v[24:25], v[24:25], 0, v[126:127]
	global_load_dwordx4 v[96:99], v[18:19], off
	global_load_dwordx4 v[104:107], v[24:25], off
	v_ashrrev_i32_e32 v18, 3, v17
	v_ashrrev_i32_e32 v19, 31, v18
	v_lshlrev_b64 v[24:25], 13, v[18:19]
	v_lshl_add_u64 v[24:25], s[2:3], 0, v[24:25]
	v_lshl_add_u64 v[132:133], v[24:25], 0, v[128:129]
	global_load_dwordx4 v[100:103], v[130:131], off
	global_load_dwordx4 v[108:111], v[132:133], off
	v_and_b32_e32 v17, 63, v138
	v_lshlrev_b32_e32 v19, 12, v26
	v_lshlrev_b32_e32 v17, 4, v17
	v_readlane_b32 s3, v255, 5
	v_mov_b32_e32 v48, v193
	v_mov_b32_e32 v49, v193
	s_movk_i32 s2, 0x110
	v_add3_u32 v143, s3, v19, v17
	v_lshl_add_u64 v[134:135], s[0:1], 0, v[126:127]
	s_sub_i32 s0, s5, 59
	v_mov_b32_e32 v50, v193
	v_mul_lo_u32 v129, v16, s2
	v_mul_lo_u32 v141, v20, s89
	v_add_u32_e32 v142, 64, v16
	v_mul_lo_u32 v145, v22, s2
	v_mul_lo_u32 v146, v18, s89
	v_add_u32_e32 v147, 64, v22
	v_or_b32_e32 v148, 31, v28
	v_add_u32_e32 v149, 0xffffff41, v28
	s_lshl_b32 s6, s4, 1
	s_mov_b32 s66, 0
	v_add3_u32 v127, s0, v27, v139
	v_mov_b32_e32 v51, v193
	v_mov_b32_e32 v52, v193
	v_mov_b32_e32 v53, v193
	v_mov_b32_e32 v54, v193
	v_mov_b32_e32 v55, v193
	v_mov_b32_e32 v56, v193
	s_waitcnt vmcnt(7)
	ds_write_b128 v143, v[0:3]
	s_waitcnt vmcnt(6)
	ds_write_b128 v143, v[4:7] offset:1024
	s_waitcnt vmcnt(5)
	ds_write_b128 v143, v[8:11] offset:2048
	s_waitcnt vmcnt(4)
	ds_write_b128 v143, v[12:15] offset:3072
	v_mov_b32_e32 v57, v193
	v_mov_b32_e32 v58, v193
	v_mov_b32_e32 v59, v193
	v_mov_b32_e32 v60, v193
	v_mov_b32_e32 v61, v193
	v_mov_b32_e32 v62, v193
	v_mov_b32_e32 v63, v193
	v_mov_b64_e32 v[32:33], v[48:49]
	v_mov_b64_e32 v[16:17], v[48:49]
	v_mov_b64_e32 v[0:1], v[48:49]
	v_lshlrev_b32_e32 v144, 6, v140
	s_add_i32 s7, s6, 2
	v_mov_b32_e32 v154, 0xf149f2ca
	v_mov_b32_e32 v151, 0
	v_mov_b64_e32 v[34:35], v[50:51]
	v_mov_b64_e32 v[36:37], v[52:53]
	v_mov_b64_e32 v[38:39], v[54:55]
	v_mov_b64_e32 v[40:41], v[56:57]
	v_mov_b64_e32 v[42:43], v[58:59]
	v_mov_b64_e32 v[44:45], v[60:61]
	v_mov_b64_e32 v[46:47], v[62:63]
	v_mov_b64_e32 v[18:19], v[50:51]
	v_mov_b64_e32 v[20:21], v[52:53]
	v_mov_b64_e32 v[22:23], v[54:55]
	v_mov_b64_e32 v[24:25], v[56:57]
	v_mov_b64_e32 v[26:27], v[58:59]
	v_mov_b64_e32 v[28:29], v[60:61]
	v_mov_b64_e32 v[30:31], v[62:63]
	v_mov_b64_e32 v[2:3], v[50:51]
	v_mov_b64_e32 v[4:5], v[52:53]
	v_mov_b64_e32 v[6:7], v[54:55]
	v_mov_b64_e32 v[8:9], v[56:57]
	v_mov_b64_e32 v[10:11], v[58:59]
	v_mov_b64_e32 v[12:13], v[60:61]
	v_mov_b64_e32 v[14:15], v[62:63]
	s_mov_b32 s8, s66
	s_branch .LBB0_978

; template <int NDT, int MODE, bool ALLON>
; DI void attn_tile(const bf16_t* Kl, int kst, const bf16_t* Vl, const bf16x8 (&q)[4], f32x16 (&O)[NDT], float& m, float& l,
;                   int kbase, int qp, int win, float cbias, const float* tab, bool lane_on) {
;     ...
;   for (int ks = 0; ks < 4; ++ks) {
;     const bf16x8 k0 = *(const bf16x8*)(Kl + lr * kst + ks * 16 + lh * 8);
;     const bf16x8 k1 = *(const bf16x8*)(Kl + (32 + lr) * kst + ks * 16 + lh * 8);
;     s[0] = MFMA32(k0, q[ks], s[0]);
;     s[1] = MFMA32(k1, q[ks], s[1]);
;   }
;   float alpha, psum = 0.f;
;   if (MODE == 0) {
;     float tmax = fmaxf(s[0][0], s[1][0]);
; #pragma unroll
;     for (int i = 1; i < 16; ++i) tmax = fmaxf(tmax, fmaxf(s[0][i], s[1][i]));
;     tmax = fmaxf(tmax, xor32(tmax)) + cbias;
;     if (!ALLON) tmax = lane_on ? tmax : -1e30f;
;     const float mn = fmaxf(m, tmax);
;     alpha = ex2(m - mn);
;     m = mn;
;     const float mc = (ALLON || lane_on) ? mn - cbias : 1e30f;
; #pragma unroll
;     for (int st = 0; st < 2; ++st)
; #pragma unroll
;       for (int i = 0; i < 16; ++i) { const float pe = ex2(s[st][i] - mc); psum += pe; s[st][i] = pe; }
;   } else {
;     float tmax = -1e30f;
; #pragma unroll
;     for (int st = 0; st < 2; ++st)
; #pragma unroll
;       for (int i = 0; i < 16; ++i) {
;         const int key = kbase + st * 32 + 8 * (i >> 2) + 4 * lh + (i & 3);
;         float v;
;         if (MODE == 1) {
;           const int dist = qp - key;
;           const bool ok = (ALLON || lane_on) && dist >= 0 && dist < win;
;           const int di = dist < 0 ? 0 : (dist > 128 ? 128 : dist);
;           v = ok ? s[st][i] + tab[di] : -1e30f;
;         } else {
;           v = (16 * key + 31 <= qp) ? s[st][i] : -1e30f;
;         }
;         s[st][i] = v;
;         tmax = fmaxf(tmax, v);
;       }
;     tmax = fmaxf(tmax, xor32(tmax));
;     const float mn = fmaxf(m, tmax);
;     alpha = ex2(m - mn);
; DI void task_attnA(const P& p, int layer, int task, bf16_t* sm, int dm) {
;     ...
;     if (kt * 64 <= qmin + 31) {
;       bf16x8 q[4];
; #pragma unroll
;       for (int ks = 0; ks < 4; ++ks) q[ks] = qlds[ks * 64];
;       if (kt * 64 + 63 + 128 <= qmin)
;         attn_tile<4, 0, true>(Kl + c * 64, 136, Vl, q, O, m, l, kt * 64, qp, 0, tab[128], tab, true);
;       else
;         attn_tile<4, 1, true>(Kl + c * 64, 136, Vl, q, O, m, l, kt * 64, qp, 1 << 30, 0.f, tab, true);
.LBB0_980:
	v_cmp_le_i32_e32 vcc, s66, v148
	s_waitcnt lgkmcnt(0)
	s_barrier
	s_and_saveexec_b64 s[0:1], vcc
	s_cbranch_execz .LBB0_977
	ds_read_b128 v[64:67], v143
	ds_read_b128 v[120:123], v143 offset:1024
	ds_read_b128 v[116:119], v143 offset:2048
	ds_read_b128 v[112:115], v143 offset:3072
	v_cmp_le_i32_e32 vcc, s66, v149
	v_lshl_add_u32 v69, v144, 1, s9
	s_and_saveexec_b64 s[2:3], vcc
	s_xor_b64 s[2:3], exec, s[2:3]
	s_cbranch_execz .LBB0_985
	v_mov_b32_e32 v68, s81
	ds_read_b32 v155, v68
	v_mov_b32_e32 v68, v195
	s_nop 0
	v_and_b32_e32 v153, 31, v68
	v_lshrrev_b32_e32 v68, 2, v68
	v_and_b32_e32 v152, 8, v68
	v_mul_u32_u24_e32 v70, 0x110, v153
	v_lshlrev_b32_e32 v68, 1, v152
	v_add3_u32 v150, v69, v70, v68
	ds_read_b128 v[68:71], v150
	ds_read_b128 v[156:159], v150 offset:32
	s_waitcnt lgkmcnt(1)
	v_mfma_f32_32x32x16_bf16 v[80:95], v[68:71], v[64:67], 0
	ds_read_b128 v[68:71], v150 offset:8704
	s_waitcnt lgkmcnt(1)
	v_mfma_f32_32x32x16_bf16 v[80:95], v[156:159], v[120:123], v[80:95]
	ds_read_b128 v[156:159], v150 offset:8736
	s_waitcnt lgkmcnt(1)
	v_mfma_f32_32x32x16_bf16 v[64:79], v[68:71], v[64:67], 0
	s_waitcnt lgkmcnt(0)
	v_mfma_f32_32x32x16_bf16 v[64:79], v[156:159], v[120:123], v[64:79]
	ds_read_b128 v[120:123], v150 offset:64
	s_waitcnt lgkmcnt(0)
	v_mfma_f32_32x32x16_bf16 v[80:95], v[120:123], v[116:119], v[80:95]
	ds_read_b128 v[120:123], v150 offset:8768
	s_waitcnt lgkmcnt(0)
	v_mfma_f32_32x32x16_bf16 v[64:79], v[120:123], v[116:119], v[64:79]
	ds_read_b128 v[116:119], v150 offset:8800
	s_waitcnt lgkmcnt(0)
	v_mfma_f32_32x32x16_bf16 v[64:79], v[116:119], v[112:115], v[64:79]
	ds_read_b128 v[116:119], v150 offset:96
	s_waitcnt lgkmcnt(0)
	v_mfma_f32_32x32x16_bf16 v[80:95], v[116:119], v[112:115], v[80:95]
	s_nop 8
	v_max3_f32 v112, v64, v65, v66
	v_max3_f32 v112, v112, v67, v68
	v_max3_f32 v112, v112, v69, v70
	v_max3_f32 v112, v112, v71, v72
	v_max3_f32 v112, v112, v73, v74
	v_max3_f32 v112, v112, v75, v76
	v_max3_f32 v112, v112, v77, v78
	v_max_f32_e32 v112, v112, v79
	v_max3_f32 v113, v80, v81, v82
	v_max3_f32 v113, v113, v83, v84
	v_max3_f32 v113, v113, v85, v86
	v_max3_f32 v113, v113, v87, v88
	v_max3_f32 v113, v113, v89, v90
	v_max3_f32 v113, v113, v91, v92
	v_max3_f32 v113, v113, v93, v94
	v_max_f32_e32 v113, v113, v95
	v_max_f32_e32 v112, v112, v113
	v_and_b32_e32 v114, 64, v231
	v_xor_b32_e32 v113, 32, v231
	v_add_u32_e32 v114, 64, v114
	v_cmp_lt_i32_e32 vcc, v113, v114
	s_nop 1
	v_cndmask_b32_e32 v113, v231, v113, vcc
	v_lshlrev_b32_e32 v113, 2, v113
	ds_bpermute_b32 v113, v113, v112
	s_waitcnt lgkmcnt(0)
	v_max_f32_e32 v113, v113, v113
	v_max_f32_e32 v112, v112, v113
	v_add_f32_e32 v112, v155, v112
	v_add_f32_e32 v113, 0x41000000, v154
	v_cmp_gt_f32_e32 vcc, v112, v113
	s_nop 1
	v_cndmask_b32_e32 v150, v154, v112, vcc
	v_sub_f32_e32 v112, v154, v150
	v_exp_f32_e32 v112, v112
	s_nop 0
	v_cmp_neq_f32_e32 vcc, 1.0, v112
	s_cbranch_vccz .LBB0_984
	v_pk_mul_f32 v[62:63], v[62:63], v[112:113] op_sel_hi:[1,0]
	v_pk_mul_f32 v[60:61], v[60:61], v[112:113] op_sel_hi:[1,0]
	v_pk_mul_f32 v[58:59], v[58:59], v[112:113] op_sel_hi:[1,0]
	v_pk_mul_f32 v[56:57], v[56:57], v[112:113] op_sel_hi:[1,0]
	v_pk_mul_f32 v[54:55], v[54:55], v[112:113] op_sel_hi:[1,0]
	v_pk_mul_f32 v[52:53], v[52:53], v[112:113] op_sel_hi:[1,0]
	v_pk_mul_f32 v[50:51], v[50:51], v[112:113] op_sel_hi:[1,0]
	v_pk_mul_f32 v[48:49], v[48:49], v[112:113] op_sel_hi:[1,0]
	v_pk_mul_f32 v[46:47], v[46:47], v[112:113] op_sel_hi:[1,0]
	v_pk_mul_f32 v[44:45], v[44:45], v[112:113] op_sel_hi:[1,0]
	v_pk_mul_f32 v[42:43], v[42:43], v[112:113] op_sel_hi:[1,0]
	v_pk_mul_f32 v[40:41], v[40:41], v[112:113] op_sel_hi:[1,0]
	v_pk_mul_f32 v[38:39], v[38:39], v[112:113] op_sel_hi:[1,0]
	v_pk_mul_f32 v[36:37], v[36:37], v[112:113] op_sel_hi:[1,0]
	v_pk_mul_f32 v[34:35], v[34:35], v[112:113] op_sel_hi:[1,0]
	v_pk_mul_f32 v[32:33], v[32:33], v[112:113] op_sel_hi:[1,0]
	v_pk_mul_f32 v[30:31], v[30:31], v[112:113] op_sel_hi:[1,0]
	v_pk_mul_f32 v[28:29], v[28:29], v[112:113] op_sel_hi:[1,0]
	v_pk_mul_f32 v[26:27], v[26:27], v[112:113] op_sel_hi:[1,0]
	v_pk_mul_f32 v[24:25], v[24:25], v[112:113] op_sel_hi:[1,0]
	v_pk_mul_f32 v[22:23], v[22:23], v[112:113] op_sel_hi:[1,0]
	v_pk_mul_f32 v[20:21], v[20:21], v[112:113] op_sel_hi:[1,0]
	v_pk_mul_f32 v[18:19], v[18:19], v[112:113] op_sel_hi:[1,0]
	v_pk_mul_f32 v[16:17], v[16:17], v[112:113] op_sel_hi:[1,0]
	v_pk_mul_f32 v[14:15], v[14:15], v[112:113] op_sel_hi:[1,0]
	v_pk_mul_f32 v[12:13], v[12:13], v[112:113] op_sel_hi:[1,0]
	v_pk_mul_f32 v[10:11], v[10:11], v[112:113] op_sel_hi:[1,0]
	v_pk_mul_f32 v[8:9], v[8:9], v[112:113] op_sel_hi:[1,0]
	v_pk_mul_f32 v[6:7], v[6:7], v[112:113] op_sel_hi:[1,0]
	v_pk_mul_f32 v[4:5], v[4:5], v[112:113] op_sel_hi:[1,0]
	v_pk_mul_f32 v[2:3], v[2:3], v[112:113] op_sel_hi:[1,0]
	v_pk_mul_f32 v[0:1], v[0:1], v[112:113] op_sel_hi:[1,0]

; template <int NDT, int MODE, bool ALLON>
; DI void attn_tile(const bf16_t* Kl, int kst, const bf16_t* Vl, const bf16x8 (&q)[4], f32x16 (&O)[NDT], float& m, float& l,
;                   int kbase, int qp, int win, float cbias, const float* tab, bool lane_on) {
;     ...
;   for (int ks = 0; ks < 4; ++ks) {
;     const bf16x8 k0 = *(const bf16x8*)(Kl + lr * kst + ks * 16 + lh * 8);
;     const bf16x8 k1 = *(const bf16x8*)(Kl + (32 + lr) * kst + ks * 16 + lh * 8);
;     s[0] = MFMA32(k0, q[ks], s[0]);
;     s[1] = MFMA32(k1, q[ks], s[1]);
;   }
;   float alpha, psum = 0.f;
;   if (MODE == 0) {
;     float tmax = fmaxf(s[0][0], s[1][0]);
; #pragma unroll
;     for (int i = 1; i < 16; ++i) tmax = fmaxf(tmax, fmaxf(s[0][i], s[1][i]));
;     tmax = fmaxf(tmax, xor32(tmax)) + cbias;
;     if (!ALLON) tmax = lane_on ? tmax : -1e30f;
;     const float mn = fmaxf(m, tmax);
;     alpha = ex2(m - mn);
;     m = mn;
;     const float mc = (ALLON || lane_on) ? mn - cbias : 1e30f;
; #pragma unroll
;     for (int st = 0; st < 2; ++st)
; #pragma unroll
;       for (int i = 0; i < 16; ++i) { const float pe = ex2(s[st][i] - mc); psum += pe; s[st][i] = pe; }
;   } else {
;     float tmax = -1e30f;
; #pragma unroll
;     for (int st = 0; st < 2; ++st)
; #pragma unroll
;       for (int i = 0; i < 16; ++i) {
;         const int key = kbase + st * 32 + 8 * (i >> 2) + 4 * lh + (i & 3);
;         float v;
;         if (MODE == 1) {
;           const int dist = qp - key;
;           const bool ok = (ALLON || lane_on) && dist >= 0 && dist < win;
;           const int di = dist < 0 ? 0 : (dist > 128 ? 128 : dist);
;           v = ok ? s[st][i] + tab[di] : -1e30f;
;         } else {
;           v = (16 * key + 31 <= qp) ? s[st][i] : -1e30f;
;         }
;         s[st][i] = v;
;         tmax = fmaxf(tmax, v);
;       }
;     tmax = fmaxf(tmax, xor32(tmax));
;     const float mn = fmaxf(m, tmax);
;     alpha = ex2(m - mn);
;     m = mn;
; #pragma unroll
;     for (int st = 0; st < 2; ++st)
; #pragma unroll
;       for (int i = 0; i < 16; ++i) {
;         const float pe = s[st][i] > -5e29f ? ex2(s[st][i] - mn) : 0.f;
;         psum += pe;
;         s[st][i] = pe;
;       }
;   }
;   l = l * alpha + psum;
; DI void task_attnA(const P& p, int layer, int task, bf16_t* sm, int dm) {
;     ...
;         attn_tile<4, 1, true>(Kl + c * 64, 136, Vl, q, O, m, l, kt * 64, qp, 1 << 30, 0.f, tab, true);
.LBB0_985:
	s_andn2_saveexec_b64 s[2:3], s[2:3]
	s_cbranch_execz .LBB0_976
	v_mov_b32_e32 v68, v195
	s_nop 0
	v_and_b32_e32 v152, 31, v68
	v_bfe_u32 v153, v68, 5, 1
	v_mul_u32_u24_e32 v68, 0x110, v152
	v_lshlrev_b32_e32 v70, 4, v153
	v_add3_u32 v150, v69, v68, v70
	ds_read_b128 v[68:71], v150
	ds_read_b128 v[156:159], v150 offset:32
	s_waitcnt lgkmcnt(1)
	v_mfma_f32_32x32x16_bf16 v[80:95], v[68:71], v[64:67], 0
	ds_read_b128 v[68:71], v150 offset:8704
	s_waitcnt lgkmcnt(1)
	v_mfma_f32_32x32x16_bf16 v[80:95], v[156:159], v[120:123], v[80:95]
	ds_read_b128 v[156:159], v150 offset:8736
	s_waitcnt lgkmcnt(1)
	v_mfma_f32_32x32x16_bf16 v[64:79], v[68:71], v[64:67], 0
	s_waitcnt lgkmcnt(0)
	v_mfma_f32_32x32x16_bf16 v[64:79], v[156:159], v[120:123], v[64:79]
	ds_read_b128 v[120:123], v150 offset:64
	ds_read_b128 v[156:159], v150 offset:8800
	s_waitcnt lgkmcnt(1)
	v_mfma_f32_32x32x16_bf16 v[80:95], v[120:123], v[116:119], v[80:95]
	ds_read_b128 v[120:123], v150 offset:8768
	s_waitcnt lgkmcnt(0)
	v_mfma_f32_32x32x16_bf16 v[64:79], v[120:123], v[116:119], v[64:79]
	ds_read_b128 v[116:119], v150 offset:96
	v_mov_b32_e32 v120, 0xf149f2ca
	s_waitcnt lgkmcnt(0)
	v_mfma_f32_32x32x16_bf16 v[80:95], v[116:119], v[112:115], v[80:95]
	v_lshlrev_b32_e32 v116, 2, v153
	v_sub_u32_e32 v123, v127, v116
	v_add_u32_e32 v117, 59, v123
	v_mov_b32_e32 v245, 0x1e014
	v_lshl_add_u32 v244, v117, 2, v245
	v_mov_b32_e32 v116, 0xf149f2ca
	v_mfma_f32_32x32x16_bf16 v[64:79], v[156:159], v[112:115], v[64:79]
	ds_read2_b32 v[196:197], v244 offset0:59 offset1:58
	ds_read2_b32 v[198:199], v244 offset0:57 offset1:56
	ds_read2_b32 v[200:201], v244 offset0:51 offset1:50
	ds_read2_b32 v[202:203], v244 offset0:49 offset1:48
	ds_read2_b32 v[204:205], v244 offset0:43 offset1:42
	ds_read2_b32 v[206:207], v244 offset0:41 offset1:40
	ds_read2_b32 v[208:209], v244 offset0:35 offset1:34
	ds_read2_b32 v[210:211], v244 offset0:33 offset1:32
	ds_read2_b32 v[212:213], v244 offset0:27 offset1:26
	ds_read2_b32 v[214:215], v244 offset0:25 offset1:24
	ds_read2_b32 v[216:217], v244 offset0:19 offset1:18
	ds_read2_b32 v[218:219], v244 offset0:17 offset1:16
	ds_read2_b32 v[236:237], v244 offset0:11 offset1:10
	ds_read2_b32 v[238:239], v244 offset0:9 offset1:8
	ds_read2_b32 v[240:241], v244 offset0:3 offset1:2
	s_waitcnt lgkmcnt(14)
	v_add_f32_e32 v120, v80, v196
	v_add_f32_e32 v116, v81, v197
	ds_read2_b32 v[242:243], v244 offset0:1 offset1:0
	s_waitcnt lgkmcnt(14)
	v_add_f32_e32 v119, v82, v198
	v_add_f32_e32 v114, v83, v199
	s_waitcnt lgkmcnt(13)
	v_add_f32_e32 v118, v84, v200
	v_add_f32_e32 v113, v85, v201
	s_waitcnt lgkmcnt(12)
	v_add_f32_e32 v117, v86, v202
	v_add_f32_e32 v112, v87, v203
	s_waitcnt lgkmcnt(11)
	v_add_f32_e32 v115, v88, v204
	v_add_f32_e32 v85, v89, v205
	s_waitcnt lgkmcnt(10)
	v_add_f32_e32 v88, v90, v206
	v_add_f32_e32 v83, v91, v207
	s_waitcnt lgkmcnt(9)
	v_add_f32_e32 v87, v92, v208
	v_add_f32_e32 v81, v93, v209
	s_waitcnt lgkmcnt(8)
	v_add_f32_e32 v86, v94, v210
	v_add_f32_e32 v80, v95, v211
	s_waitcnt lgkmcnt(7)
	v_add_f32_e32 v84, v64, v212
	v_add_f32_e32 v82, v65, v213
	s_waitcnt lgkmcnt(6)
	v_add_f32_e32 v89, v66, v214
	v_add_f32_e32 v65, v67, v215
	s_waitcnt lgkmcnt(5)
	v_add_f32_e32 v67, v68, v216
	v_add_f32_e32 v66, v69, v217
	s_waitcnt lgkmcnt(4)
	v_add_f32_e32 v69, v70, v218
	v_add_f32_e32 v68, v71, v219
	s_waitcnt lgkmcnt(3)
	v_add_f32_e32 v71, v72, v236
	v_add_f32_e32 v70, v73, v237
	s_waitcnt lgkmcnt(2)
	v_add_f32_e32 v73, v74, v238
	v_add_f32_e32 v72, v75, v239
	s_waitcnt lgkmcnt(1)
	v_add_f32_e32 v92, v76, v240
	v_add_f32_e32 v91, v77, v241
	s_waitcnt lgkmcnt(0)
	v_add_f32_e32 v122, v78, v242
	v_add_f32_e32 v121, v79, v243
	v_max3_f32 v64, v120, s93, v116
	v_max3_f32 v64, v64, v119, v114
	v_max3_f32 v64, v64, v118, v113
	v_max3_f32 v64, v64, v117, v112
	v_max3_f32 v64, v64, v115, v85
	v_max3_f32 v64, v64, v88, v83
	v_max3_f32 v64, v64, v87, v81
	v_max3_f32 v64, v64, v86, v80
	v_max3_f32 v64, v64, v84, v82
	v_max3_f32 v64, v64, v89, v65
	v_max3_f32 v64, v64, v67, v66
	v_max3_f32 v64, v64, v69, v68
	v_and_b32_e32 v75, 64, v231
	v_max3_f32 v64, v64, v71, v70
	v_xor_b32_e32 v74, 32, v231
	v_add_u32_e32 v75, 64, v75
	v_max3_f32 v64, v64, v73, v72
	v_cmp_lt_i32_e32 vcc, v74, v75
	v_max3_f32 v64, v64, v92, v91
	v_max3_f32 v64, v64, v122, v121
	v_cndmask_b32_e32 v74, v231, v74, vcc
	v_lshlrev_b32_e32 v74, 2, v74
	ds_bpermute_b32 v74, v74, v64
	s_waitcnt lgkmcnt(0)
	v_max_f32_e32 v64, v64, v74
	v_add_f32_e32 v74, 0x41000000, v154
	v_cmp_gt_f32_e32 vcc, v64, v74
	s_nop 1
	v_cndmask_b32_e32 v150, v154, v64, vcc
	v_sub_f32_e32 v64, v154, v150
	v_exp_f32_e32 v64, v64
	s_nop 0
	v_cmp_neq_f32_e32 vcc, 1.0, v64
	s_cbranch_vccz .LBB0_975
	v_pk_mul_f32 v[62:63], v[62:63], v[64:65] op_sel_hi:[1,0]
	v_pk_mul_f32 v[60:61], v[60:61], v[64:65] op_sel_hi:[1,0]
	v_pk_mul_f32 v[58:59], v[58:59], v[64:65] op_sel_hi:[1,0]
	v_pk_mul_f32 v[56:57], v[56:57], v[64:65] op_sel_hi:[1,0]
	v_pk_mul_f32 v[54:55], v[54:55], v[64:65] op_sel_hi:[1,0]
	v_pk_mul_f32 v[52:53], v[52:53], v[64:65] op_sel_hi:[1,0]
	v_pk_mul_f32 v[50:51], v[50:51], v[64:65] op_sel_hi:[1,0]
	v_pk_mul_f32 v[48:49], v[48:49], v[64:65] op_sel_hi:[1,0]
	v_pk_mul_f32 v[46:47], v[46:47], v[64:65] op_sel_hi:[1,0]
	v_pk_mul_f32 v[44:45], v[44:45], v[64:65] op_sel_hi:[1,0]
	v_pk_mul_f32 v[42:43], v[42:43], v[64:65] op_sel_hi:[1,0]
	v_pk_mul_f32 v[40:41], v[40:41], v[64:65] op_sel_hi:[1,0]
	v_pk_mul_f32 v[38:39], v[38:39], v[64:65] op_sel_hi:[1,0]
	v_pk_mul_f32 v[36:37], v[36:37], v[64:65] op_sel_hi:[1,0]
	v_pk_mul_f32 v[34:35], v[34:35], v[64:65] op_sel_hi:[1,0]
	v_pk_mul_f32 v[32:33], v[32:33], v[64:65] op_sel_hi:[1,0]
	v_pk_mul_f32 v[30:31], v[30:31], v[64:65] op_sel_hi:[1,0]
	v_pk_mul_f32 v[28:29], v[28:29], v[64:65] op_sel_hi:[1,0]
	v_pk_mul_f32 v[26:27], v[26:27], v[64:65] op_sel_hi:[1,0]
	v_pk_mul_f32 v[24:25], v[24:25], v[64:65] op_sel_hi:[1,0]
	v_pk_mul_f32 v[22:23], v[22:23], v[64:65] op_sel_hi:[1,0]
	v_pk_mul_f32 v[20:21], v[20:21], v[64:65] op_sel_hi:[1,0]
	v_pk_mul_f32 v[18:19], v[18:19], v[64:65] op_sel_hi:[1,0]
	v_pk_mul_f32 v[16:17], v[16:17], v[64:65] op_sel_hi:[1,0]
	v_pk_mul_f32 v[14:15], v[14:15], v[64:65] op_sel_hi:[1,0]
	v_pk_mul_f32 v[12:13], v[12:13], v[64:65] op_sel_hi:[1,0]
	v_pk_mul_f32 v[10:11], v[10:11], v[64:65] op_sel_hi:[1,0]
	v_pk_mul_f32 v[8:9], v[8:9], v[64:65] op_sel_hi:[1,0]
	v_pk_mul_f32 v[6:7], v[6:7], v[64:65] op_sel_hi:[1,0]
	v_pk_mul_f32 v[4:5], v[4:5], v[64:65] op_sel_hi:[1,0]
	v_pk_mul_f32 v[2:3], v[2:3], v[64:65] op_sel_hi:[1,0]
	v_pk_mul_f32 v[0:1], v[0:1], v[64:65] op_sel_hi:[1,0]
	s_branch .LBB0_975
